# all GEMM K-loops MFMA order variant nk_m
# baseline (speedup 1.0000x reference)
; #define PG8_STAGE(bufoff, gbase, voff) do { _Pragma("unroll") for (int _i = 0; _i < 2; ++_i) \
;         __builtin_amdgcn_global_load_lds((const unsigned*)((const char*)(gbase) + (voff)[_i]), (PG8_LAS unsigned*)(lds + (bufoff) + ldsw + _i * 8192), 16, 0, 0); } while (0)
; #define PG8_LDA(dst, b, h) do { _Pragma("unroll") for (int m = 0; m < 4; ++m) _Pragma("unroll") for (int k = 0; k < 2; ++k) dst[m][k] = *(const PG8_LAS bf16x8*)(lds + PG8_SA(b, h) + aoff + m * 2048 + k * 1024); } while (0)
; #define PG8_LDB(dst, b, h) do { _Pragma("unroll") for (int n = 0; n < 2; ++n) _Pragma("unroll") for (int k = 0; k < 2; ++k) dst[n][k] = *(const PG8_LAS bf16x8*)(lds + PG8_SB(b, h) + boff + n * 2048 + k * 1024); } while (0)
; #define PG8_MMA(ai, bj, At, Bt) do { __builtin_amdgcn_s_setprio(1); _Pragma("unroll") for (int m = 0; m < 4; ++m) _Pragma("unroll") for (int n = 0; n < 2; ++n) _Pragma("unroll") for (int k = 0; k < 2; ++k) \
;         acc[ai][bj][m][n] = __builtin_amdgcn_mfma_f32_16x16x32_bf16(Bt[n][k], At[m][k], acc[ai][bj][m][n], 0, 0, 0); __builtin_amdgcn_s_setprio(0); } while (0)
; #define PG8_WAIT_V(n) asm volatile("s_waitcnt vmcnt(" #n ")" ::: "memory")
; #define PG8_WAIT_L(n) asm volatile("s_waitcnt lgkmcnt(" #n ")" ::: "memory")
; #define PG8_BAR __builtin_amdgcn_s_barrier()
; #define PG8_SCHED __builtin_amdgcn_sched_barrier(0)
; template <class Epi, class Sched, bool ALIGN_EPI = false, bool SP2 = false>
; __device__ __forceinline__ void gemm_phase(PG8_LAS unsigned char* lds, const Gemm g, const Sched& S, const Epi& E) {
;     ...
;             PG8_LDB(B0, 0, 0); PG8_LDB(B1, 0, 1); PG8_SCHED; PG8_LDA(At, 0, 0); PG8_STAGE(PG8_SA(1, 1), a1 + hstep, voffA);
;             PG8_WAIT_V(8); PG8_WAIT_L(0); PG8_BAR; PG8_MMA(0, 0, At, B0); PG8_MMA(0, 1, At, B1); PG8_BAR; PG8_SCHED;
;             PG8_LDA(At, 0, 1); PG8_STAGE(PG8_SB(0, 0), b2, voffB); PG8_STAGE(PG8_SB(0, 1), b2 + hstep, voffB); PG8_STAGE(PG8_SA(0, 0), a2, voffA);
.LBB11_228:
	ds_read_b128 v[152:155], v149
	ds_read_b128 v[156:159], v149 offset:1024
	ds_read_b128 v[160:163], v149 offset:2048
	ds_read_b128 v[164:167], v149 offset:3072
	ds_read_b128 v[168:171], v150
	ds_read_b128 v[172:175], v150 offset:1024
	ds_read_b128 v[176:179], v150 offset:2048
	ds_read_b128 v[180:183], v150 offset:3072
	s_add_u32 s30, s28, 0xfff80080
	s_addc_u32 s31, s29, -1
	s_cmp_eq_u32 s61, 28
	s_cselect_b32 s35, s21, s31
	s_cselect_b32 s34, s57, s30
	s_cselect_b32 s31, s19, s60
	s_cselect_b32 s30, s58, s59
	v_lshl_add_u64 v[144:145], s[28:29], 0, v[140:141]
	s_add_i32 m0, s27, 0xc000
	ds_read_b128 v[184:187], v151
	ds_read_b128 v[188:191], v151 offset:1024
	ds_read_b128 v[192:195], v151 offset:2048
	ds_read_b128 v[196:199], v151 offset:3072
	ds_read_b128 v[200:203], v151 offset:4096
	ds_read_b128 v[204:207], v151 offset:5120
	ds_read_b128 v[210:213], v151 offset:6144
	ds_read_b128 v[214:217], v151 offset:7168
	global_load_lds_dwordx4 v[144:145], off
	v_lshl_add_u64 v[144:145], s[28:29], 0, v[142:143]
	s_add_i32 m0, s27, 0xe000
	s_nop 0
	global_load_lds_dwordx4 v[144:145], off
	s_waitcnt vmcnt(8)
	s_waitcnt lgkmcnt(0)
	s_barrier
	s_setprio 1
	s_waitcnt lgkmcnt(0)
	v_mfma_f32_16x16x32_bf16 v[126:129], v[152:155], v[184:187], v[126:129]
	v_mfma_f32_16x16x32_bf16 v[118:121], v[152:155], v[192:195], v[118:121]
	v_mfma_f32_16x16x32_bf16 v[102:105], v[152:155], v[200:203], v[102:105]
	v_mfma_f32_16x16x32_bf16 v[86:89], v[152:155], v[210:213], v[86:89]
	v_mfma_f32_16x16x32_bf16 v[122:125], v[160:163], v[184:187], v[122:125]
	v_mfma_f32_16x16x32_bf16 v[110:113], v[160:163], v[192:195], v[110:113]
	v_mfma_f32_16x16x32_bf16 v[94:97], v[160:163], v[200:203], v[94:97]
	v_mfma_f32_16x16x32_bf16 v[78:81], v[160:163], v[210:213], v[78:81]
	v_mfma_f32_16x16x32_bf16 v[126:129], v[156:159], v[188:191], v[126:129]
	v_mfma_f32_16x16x32_bf16 v[118:121], v[156:159], v[196:199], v[118:121]
	v_mfma_f32_16x16x32_bf16 v[102:105], v[156:159], v[204:207], v[102:105]
	v_mfma_f32_16x16x32_bf16 v[86:89], v[156:159], v[214:217], v[86:89]
	v_mfma_f32_16x16x32_bf16 v[122:125], v[164:167], v[188:191], v[122:125]
	v_mfma_f32_16x16x32_bf16 v[110:113], v[164:167], v[196:199], v[110:113]
	v_mfma_f32_16x16x32_bf16 v[94:97], v[164:167], v[204:207], v[94:97]
	v_mfma_f32_16x16x32_bf16 v[78:81], v[164:167], v[214:217], v[78:81]
	s_setprio 0
	s_setprio 1
	v_mfma_f32_16x16x32_bf16 v[114:117], v[168:171], v[184:187], v[114:117]
	v_mfma_f32_16x16x32_bf16 v[98:101], v[168:171], v[192:195], v[98:101]
	v_mfma_f32_16x16x32_bf16 v[82:85], v[168:171], v[200:203], v[82:85]
	v_mfma_f32_16x16x32_bf16 v[70:73], v[168:171], v[210:213], v[70:73]
	v_mfma_f32_16x16x32_bf16 v[106:109], v[176:179], v[184:187], v[106:109]
	v_mfma_f32_16x16x32_bf16 v[90:93], v[176:179], v[192:195], v[90:93]
	v_mfma_f32_16x16x32_bf16 v[74:77], v[176:179], v[200:203], v[74:77]
	v_mfma_f32_16x16x32_bf16 v[66:69], v[176:179], v[210:213], v[66:69]
	v_mfma_f32_16x16x32_bf16 v[114:117], v[172:175], v[188:191], v[114:117]
	v_mfma_f32_16x16x32_bf16 v[98:101], v[172:175], v[196:199], v[98:101]
	v_mfma_f32_16x16x32_bf16 v[82:85], v[172:175], v[204:207], v[82:85]
	v_mfma_f32_16x16x32_bf16 v[70:73], v[172:175], v[214:217], v[70:73]
	v_mfma_f32_16x16x32_bf16 v[106:109], v[180:183], v[188:191], v[106:109]
	v_mfma_f32_16x16x32_bf16 v[90:93], v[180:183], v[196:199], v[90:93]
	v_mfma_f32_16x16x32_bf16 v[74:77], v[180:183], v[204:207], v[74:77]
	v_mfma_f32_16x16x32_bf16 v[66:69], v[180:183], v[214:217], v[66:69]
	s_setprio 0
	s_barrier
	s_add_i32 s62, s50, s37
	v_lshl_add_u64 v[144:145], s[30:31], 0, v[134:135]
	s_mov_b32 m0, s62
	ds_read_b128 v[184:187], v151 offset:16384
	ds_read_b128 v[188:191], v151 offset:17408
	ds_read_b128 v[192:195], v151 offset:18432
	ds_read_b128 v[196:199], v151 offset:19456
	ds_read_b128 v[200:203], v151 offset:20480
	ds_read_b128 v[204:207], v151 offset:21504
	ds_read_b128 v[210:213], v151 offset:22528
	ds_read_b128 v[214:217], v151 offset:23552
	global_load_lds_dwordx4 v[144:145], off
	s_add_i32 m0, s62, 0x2000
	s_add_u32 s62, s30, 0x80000
	v_lshl_add_u64 v[218:219], s[30:31], 0, v[130:131]
	s_addc_u32 s63, s31, 0
	s_add_i32 s64, s51, s37
	global_load_lds_dwordx4 v[218:219], off
	v_lshl_add_u64 v[220:221], s[62:63], 0, v[134:135]
	s_mov_b32 m0, s64
	v_lshl_add_u64 v[222:223], s[34:35], 0, v[132:133]
	global_load_lds_dwordx4 v[220:221], off
	v_lshl_add_u64 v[220:221], s[62:63], 0, v[130:131]
	s_add_i32 m0, s64, 0x2000
	s_nop 0
	global_load_lds_dwordx4 v[220:221], off
	v_lshl_add_u64 v[220:221], s[34:35], 0, v[136:137]
	s_mov_b32 m0, s27
	s_nop 0
	global_load_lds_dwordx4 v[220:221], off
	s_mov_b32 m0, s39
	s_nop 0
	global_load_lds_dwordx4 v[222:223], off
	s_waitcnt vmcnt(8)
	s_waitcnt lgkmcnt(0)
	s_barrier
; #define PG8_STAGE(bufoff, gbase, voff) do { _Pragma("unroll") for (int _i = 0; _i < 2; ++_i) \
;         __builtin_amdgcn_global_load_lds((const unsigned*)((const char*)(gbase) + (voff)[_i]), (PG8_LAS unsigned*)(lds + (bufoff) + ldsw + _i * 8192), 16, 0, 0); } while (0)
; #define PG8_LDA(dst, b, h) do { _Pragma("unroll") for (int m = 0; m < 4; ++m) _Pragma("unroll") for (int k = 0; k < 2; ++k) dst[m][k] = *(const PG8_LAS bf16x8*)(lds + PG8_SA(b, h) + aoff + m * 2048 + k * 1024); } while (0)
; #define PG8_LDB(dst, b, h) do { _Pragma("unroll") for (int n = 0; n < 2; ++n) _Pragma("unroll") for (int k = 0; k < 2; ++k) dst[n][k] = *(const PG8_LAS bf16x8*)(lds + PG8_SB(b, h) + boff + n * 2048 + k * 1024); } while (0)
; #define PG8_MMA(ai, bj, At, Bt) do { __builtin_amdgcn_s_setprio(1); _Pragma("unroll") for (int m = 0; m < 4; ++m) _Pragma("unroll") for (int n = 0; n < 2; ++n) _Pragma("unroll") for (int k = 0; k < 2; ++k) \
;         acc[ai][bj][m][n] = __builtin_amdgcn_mfma_f32_16x16x32_bf16(Bt[n][k], At[m][k], acc[ai][bj][m][n], 0, 0, 0); __builtin_amdgcn_s_setprio(0); } while (0)
; #define PG8_WAIT_V(n) asm volatile("s_waitcnt vmcnt(" #n ")" ::: "memory")
; #define PG8_WAIT_L(n) asm volatile("s_waitcnt lgkmcnt(" #n ")" ::: "memory")
; #define PG8_BAR __builtin_amdgcn_s_barrier()
; #define PG8_SCHED __builtin_amdgcn_sched_barrier(0)
; template <class Epi, class Sched, bool ALIGN_EPI = false, bool SP2 = false>
; __device__ __forceinline__ void gemm_phase(PG8_LAS unsigned char* lds, const Gemm g, const Sched& S, const Epi& E) {
;     ...
;             PG8_WAIT_V(8); PG8_WAIT_L(0); PG8_BAR; PG8_MMA(1, 0, At, B0); PG8_MMA(1, 1, At, B1); PG8_BAR; PG8_SCHED;
;             PG8_LDB(B0, 1, 0); PG8_LDB(B1, 1, 1); PG8_SCHED; PG8_LDA(At, 1, 0); PG8_STAGE(PG8_SA(0, 1), a2 + hstep, voffA);
;             PG8_WAIT_V(8); PG8_WAIT_L(0); PG8_BAR; PG8_MMA(0, 0, At, B0); PG8_MMA(0, 1, At, B1); PG8_BAR; PG8_SCHED;
	s_setprio 1
	s_waitcnt lgkmcnt(0)
	v_mfma_f32_16x16x32_bf16 v[62:65], v[152:155], v[184:187], v[62:65]
	v_mfma_f32_16x16x32_bf16 v[54:57], v[152:155], v[192:195], v[54:57]
	v_mfma_f32_16x16x32_bf16 v[38:41], v[152:155], v[200:203], v[38:41]
	v_mfma_f32_16x16x32_bf16 v[22:25], v[152:155], v[210:213], v[22:25]
	v_mfma_f32_16x16x32_bf16 v[58:61], v[160:163], v[184:187], v[58:61]
	v_mfma_f32_16x16x32_bf16 v[46:49], v[160:163], v[192:195], v[46:49]
	v_mfma_f32_16x16x32_bf16 v[30:33], v[160:163], v[200:203], v[30:33]
	v_mfma_f32_16x16x32_bf16 v[14:17], v[160:163], v[210:213], v[14:17]
	v_mfma_f32_16x16x32_bf16 v[62:65], v[156:159], v[188:191], v[62:65]
	v_mfma_f32_16x16x32_bf16 v[54:57], v[156:159], v[196:199], v[54:57]
	v_mfma_f32_16x16x32_bf16 v[38:41], v[156:159], v[204:207], v[38:41]
	v_mfma_f32_16x16x32_bf16 v[22:25], v[156:159], v[214:217], v[22:25]
	v_mfma_f32_16x16x32_bf16 v[58:61], v[164:167], v[188:191], v[58:61]
	v_mfma_f32_16x16x32_bf16 v[46:49], v[164:167], v[196:199], v[46:49]
	v_mfma_f32_16x16x32_bf16 v[30:33], v[164:167], v[204:207], v[30:33]
	v_mfma_f32_16x16x32_bf16 v[14:17], v[164:167], v[214:217], v[14:17]
	s_setprio 0
	s_setprio 1
	v_mfma_f32_16x16x32_bf16 v[50:53], v[168:171], v[184:187], v[50:53]
	v_mfma_f32_16x16x32_bf16 v[34:37], v[168:171], v[192:195], v[34:37]
	v_mfma_f32_16x16x32_bf16 v[18:21], v[168:171], v[200:203], v[18:21]
	v_mfma_f32_16x16x32_bf16 v[6:9], v[168:171], v[210:213], v[6:9]
	v_mfma_f32_16x16x32_bf16 v[42:45], v[176:179], v[184:187], v[42:45]
	v_mfma_f32_16x16x32_bf16 v[26:29], v[176:179], v[192:195], v[26:29]
	v_mfma_f32_16x16x32_bf16 v[10:13], v[176:179], v[200:203], v[10:13]
	v_mfma_f32_16x16x32_bf16 v[2:5], v[176:179], v[210:213], v[2:5]
	v_mfma_f32_16x16x32_bf16 v[50:53], v[172:175], v[188:191], v[50:53]
	v_mfma_f32_16x16x32_bf16 v[34:37], v[172:175], v[196:199], v[34:37]
	v_mfma_f32_16x16x32_bf16 v[18:21], v[172:175], v[204:207], v[18:21]
	v_mfma_f32_16x16x32_bf16 v[6:9], v[172:175], v[214:217], v[6:9]
	v_mfma_f32_16x16x32_bf16 v[42:45], v[180:183], v[188:191], v[42:45]
	v_mfma_f32_16x16x32_bf16 v[26:29], v[180:183], v[196:199], v[26:29]
	v_mfma_f32_16x16x32_bf16 v[10:13], v[180:183], v[204:207], v[10:13]
	v_mfma_f32_16x16x32_bf16 v[2:5], v[180:183], v[214:217], v[2:5]
	s_setprio 0
	s_barrier
	s_add_i32 s62, 0, 0x18000
	s_add_i32 s63, 0, 0x1c000
	v_add_u32_e32 v164, s62, v147
	v_add_u32_e32 v180, s63, v147
	ds_read_b128 v[152:155], v164
	ds_read_b128 v[156:159], v164 offset:1024
	ds_read_b128 v[160:163], v164 offset:2048
	ds_read_b128 v[164:167], v164 offset:3072
	ds_read_b128 v[168:171], v180
	ds_read_b128 v[172:175], v180 offset:1024
	ds_read_b128 v[176:179], v180 offset:2048
	ds_read_b128 v[180:183], v180 offset:3072
	s_add_u32 s34, s34, 0x80000
	s_addc_u32 s35, s35, 0
	s_mov_b32 m0, s40
	v_lshl_add_u64 v[224:225], s[34:35], 0, v[136:137]
	ds_read_b128 v[184:187], v151 offset:32768
	ds_read_b128 v[188:191], v151 offset:33792
	ds_read_b128 v[192:195], v151 offset:34816
	ds_read_b128 v[196:199], v151 offset:35840
	ds_read_b128 v[200:203], v151 offset:36864
	ds_read_b128 v[204:207], v151 offset:37888
	ds_read_b128 v[210:213], v151 offset:38912
	ds_read_b128 v[214:217], v151 offset:39936
	global_load_lds_dwordx4 v[224:225], off
	v_lshl_add_u64 v[224:225], s[34:35], 0, v[132:133]
	s_mov_b32 m0, s41
	s_nop 0
	global_load_lds_dwordx4 v[224:225], off
	s_waitcnt vmcnt(8)
	s_waitcnt lgkmcnt(0)
	s_barrier
	s_setprio 1
	s_waitcnt lgkmcnt(0)
	v_mfma_f32_16x16x32_bf16 v[126:129], v[152:155], v[184:187], v[126:129]
	v_mfma_f32_16x16x32_bf16 v[118:121], v[152:155], v[192:195], v[118:121]
	v_mfma_f32_16x16x32_bf16 v[102:105], v[152:155], v[200:203], v[102:105]
	v_mfma_f32_16x16x32_bf16 v[86:89], v[152:155], v[210:213], v[86:89]
	v_mfma_f32_16x16x32_bf16 v[122:125], v[160:163], v[184:187], v[122:125]
	v_mfma_f32_16x16x32_bf16 v[110:113], v[160:163], v[192:195], v[110:113]
	v_mfma_f32_16x16x32_bf16 v[94:97], v[160:163], v[200:203], v[94:97]
	v_mfma_f32_16x16x32_bf16 v[78:81], v[160:163], v[210:213], v[78:81]
	v_mfma_f32_16x16x32_bf16 v[126:129], v[156:159], v[188:191], v[126:129]
	v_mfma_f32_16x16x32_bf16 v[118:121], v[156:159], v[196:199], v[118:121]
	v_mfma_f32_16x16x32_bf16 v[102:105], v[156:159], v[204:207], v[102:105]
	v_mfma_f32_16x16x32_bf16 v[86:89], v[156:159], v[214:217], v[86:89]
	v_mfma_f32_16x16x32_bf16 v[122:125], v[164:167], v[188:191], v[122:125]
	v_mfma_f32_16x16x32_bf16 v[110:113], v[164:167], v[196:199], v[110:113]
	v_mfma_f32_16x16x32_bf16 v[94:97], v[164:167], v[204:207], v[94:97]
	v_mfma_f32_16x16x32_bf16 v[78:81], v[164:167], v[214:217], v[78:81]
	s_setprio 0
	s_setprio 1
	v_mfma_f32_16x16x32_bf16 v[114:117], v[168:171], v[184:187], v[114:117]
	v_mfma_f32_16x16x32_bf16 v[98:101], v[168:171], v[192:195], v[98:101]
	v_mfma_f32_16x16x32_bf16 v[82:85], v[168:171], v[200:203], v[82:85]
	v_mfma_f32_16x16x32_bf16 v[70:73], v[168:171], v[210:213], v[70:73]
	v_mfma_f32_16x16x32_bf16 v[106:109], v[176:179], v[184:187], v[106:109]
	v_mfma_f32_16x16x32_bf16 v[90:93], v[176:179], v[192:195], v[90:93]
	v_mfma_f32_16x16x32_bf16 v[74:77], v[176:179], v[200:203], v[74:77]
	v_mfma_f32_16x16x32_bf16 v[66:69], v[176:179], v[210:213], v[66:69]
	v_mfma_f32_16x16x32_bf16 v[114:117], v[172:175], v[188:191], v[114:117]
	v_mfma_f32_16x16x32_bf16 v[98:101], v[172:175], v[196:199], v[98:101]
	v_mfma_f32_16x16x32_bf16 v[82:85], v[172:175], v[204:207], v[82:85]
	v_mfma_f32_16x16x32_bf16 v[70:73], v[172:175], v[214:217], v[70:73]
	v_mfma_f32_16x16x32_bf16 v[106:109], v[180:183], v[188:191], v[106:109]
	v_mfma_f32_16x16x32_bf16 v[90:93], v[180:183], v[196:199], v[90:93]
	v_mfma_f32_16x16x32_bf16 v[74:77], v[180:183], v[204:207], v[74:77]
	v_mfma_f32_16x16x32_bf16 v[66:69], v[180:183], v[214:217], v[66:69]
	s_setprio 0
	s_barrier
; #define PG8_STAGE(bufoff, gbase, voff) do { _Pragma("unroll") for (int _i = 0; _i < 2; ++_i) \
;         __builtin_amdgcn_global_load_lds((const unsigned*)((const char*)(gbase) + (voff)[_i]), (PG8_LAS unsigned*)(lds + (bufoff) + ldsw + _i * 8192), 16, 0, 0); } while (0)
; #define PG8_LDA(dst, b, h) do { _Pragma("unroll") for (int m = 0; m < 4; ++m) _Pragma("unroll") for (int k = 0; k < 2; ++k) dst[m][k] = *(const PG8_LAS bf16x8*)(lds + PG8_SA(b, h) + aoff + m * 2048 + k * 1024); } while (0)
; #define PG8_MMA(ai, bj, At, Bt) do { __builtin_amdgcn_s_setprio(1); _Pragma("unroll") for (int m = 0; m < 4; ++m) _Pragma("unroll") for (int n = 0; n < 2; ++n) _Pragma("unroll") for (int k = 0; k < 2; ++k) \
;         acc[ai][bj][m][n] = __builtin_amdgcn_mfma_f32_16x16x32_bf16(Bt[n][k], At[m][k], acc[ai][bj][m][n], 0, 0, 0); __builtin_amdgcn_s_setprio(0); } while (0)
; #define PG8_WAIT_V(n) asm volatile("s_waitcnt vmcnt(" #n ")" ::: "memory")
; #define PG8_WAIT_L(n) asm volatile("s_waitcnt lgkmcnt(" #n ")" ::: "memory")
; #define PG8_BAR __builtin_amdgcn_s_barrier()
; #define PG8_SCHED __builtin_amdgcn_sched_barrier(0)
; template <class Epi, class Sched, bool ALIGN_EPI = false, bool SP2 = false>
; __device__ __forceinline__ void gemm_phase(PG8_LAS unsigned char* lds, const Gemm g, const Sched& S, const Epi& E) {
;     ...
;             PG8_LDA(At, 1, 1); PG8_STAGE(PG8_SB(1, 0), b3, voffB); PG8_STAGE(PG8_SB(1, 1), b3 + hstep, voffB); PG8_STAGE(PG8_SA(1, 0), a3, voffA);
;             PG8_WAIT_V(8); PG8_WAIT_L(0); PG8_BAR; PG8_MMA(1, 0, At, B0); PG8_MMA(1, 1, At, B1); PG8_BAR; PG8_SCHED;
	s_add_i32 s34, s62, s37
	v_lshl_add_u64 v[144:145], v[144:145], 0, s[6:7]
	s_mov_b32 m0, s34
	ds_read_b128 v[184:187], v151 offset:49152
	ds_read_b128 v[188:191], v151 offset:50176
	ds_read_b128 v[192:195], v151 offset:51200
	ds_read_b128 v[196:199], v151 offset:52224
	ds_read_b128 v[200:203], v151 offset:53248
	ds_read_b128 v[204:207], v151 offset:54272
	ds_read_b128 v[210:213], v151 offset:55296
	ds_read_b128 v[214:217], v151 offset:56320
	global_load_lds_dwordx4 v[144:145], off
	s_add_i32 m0, s34, 0x2000
	s_add_u32 s30, s30, 0x80080
	v_lshl_add_u64 v[144:145], v[218:219], 0, s[6:7]
	s_addc_u32 s31, s31, 0
	s_add_i32 s34, s63, s37
	global_load_lds_dwordx4 v[144:145], off
	v_lshl_add_u64 v[144:145], s[30:31], 0, v[134:135]
	s_mov_b32 m0, s34
	s_nop 0
	global_load_lds_dwordx4 v[144:145], off
	v_lshl_add_u64 v[144:145], s[30:31], 0, v[130:131]
	s_add_i32 m0, s34, 0x2000
	s_nop 0
	global_load_lds_dwordx4 v[144:145], off
	v_lshl_add_u64 v[144:145], v[220:221], 0, s[6:7]
	s_mov_b32 m0, s48
	s_nop 0
	global_load_lds_dwordx4 v[144:145], off
	v_lshl_add_u64 v[144:145], v[222:223], 0, s[6:7]
	s_mov_b32 m0, s49
	s_nop 0
	global_load_lds_dwordx4 v[144:145], off
	s_waitcnt vmcnt(8)
	s_waitcnt lgkmcnt(0)
	s_barrier
	s_setprio 1
	s_waitcnt lgkmcnt(0)
	v_mfma_f32_16x16x32_bf16 v[62:65], v[152:155], v[184:187], v[62:65]
	v_mfma_f32_16x16x32_bf16 v[54:57], v[152:155], v[192:195], v[54:57]
	v_mfma_f32_16x16x32_bf16 v[38:41], v[152:155], v[200:203], v[38:41]
	v_mfma_f32_16x16x32_bf16 v[22:25], v[152:155], v[210:213], v[22:25]
	v_mfma_f32_16x16x32_bf16 v[58:61], v[160:163], v[184:187], v[58:61]
	v_mfma_f32_16x16x32_bf16 v[46:49], v[160:163], v[192:195], v[46:49]
	v_mfma_f32_16x16x32_bf16 v[30:33], v[160:163], v[200:203], v[30:33]
	v_mfma_f32_16x16x32_bf16 v[14:17], v[160:163], v[210:213], v[14:17]
	v_mfma_f32_16x16x32_bf16 v[62:65], v[156:159], v[188:191], v[62:65]
	v_mfma_f32_16x16x32_bf16 v[54:57], v[156:159], v[196:199], v[54:57]
	v_mfma_f32_16x16x32_bf16 v[38:41], v[156:159], v[204:207], v[38:41]
	v_mfma_f32_16x16x32_bf16 v[22:25], v[156:159], v[214:217], v[22:25]
	v_mfma_f32_16x16x32_bf16 v[58:61], v[164:167], v[188:191], v[58:61]
	v_mfma_f32_16x16x32_bf16 v[46:49], v[164:167], v[196:199], v[46:49]
	v_mfma_f32_16x16x32_bf16 v[30:33], v[164:167], v[204:207], v[30:33]
	v_mfma_f32_16x16x32_bf16 v[14:17], v[164:167], v[214:217], v[14:17]
	s_setprio 0
	s_setprio 1
	v_mfma_f32_16x16x32_bf16 v[50:53], v[168:171], v[184:187], v[50:53]
	v_mfma_f32_16x16x32_bf16 v[34:37], v[168:171], v[192:195], v[34:37]
	v_mfma_f32_16x16x32_bf16 v[18:21], v[168:171], v[200:203], v[18:21]
	v_mfma_f32_16x16x32_bf16 v[6:9], v[168:171], v[210:213], v[6:9]
	v_mfma_f32_16x16x32_bf16 v[42:45], v[176:179], v[184:187], v[42:45]
	v_mfma_f32_16x16x32_bf16 v[26:29], v[176:179], v[192:195], v[26:29]
	v_mfma_f32_16x16x32_bf16 v[10:13], v[176:179], v[200:203], v[10:13]
	v_mfma_f32_16x16x32_bf16 v[2:5], v[176:179], v[210:213], v[2:5]
	v_mfma_f32_16x16x32_bf16 v[50:53], v[172:175], v[188:191], v[50:53]
	v_mfma_f32_16x16x32_bf16 v[34:37], v[172:175], v[196:199], v[34:37]
	v_mfma_f32_16x16x32_bf16 v[18:21], v[172:175], v[204:207], v[18:21]
	v_mfma_f32_16x16x32_bf16 v[6:9], v[172:175], v[214:217], v[6:9]
	v_mfma_f32_16x16x32_bf16 v[42:45], v[180:183], v[188:191], v[42:45]
	v_mfma_f32_16x16x32_bf16 v[26:29], v[180:183], v[196:199], v[26:29]
	v_mfma_f32_16x16x32_bf16 v[10:13], v[180:183], v[204:207], v[10:13]
	v_mfma_f32_16x16x32_bf16 v[2:5], v[180:183], v[214:217], v[2:5]
	s_setprio 0
	s_barrier
	s_add_i32 s61, s61, 2
	s_add_u32 s28, s28, 0x100
	s_addc_u32 s29, s29, 0
	s_add_u32 s59, s59, 0x100
	s_addc_u32 s60, s60, 0
	s_cmp_gt_u32 s61, 29
	s_cbranch_scc0 .LBB11_228
	s_and_b64 vcc, exec, s[8:9]
	s_cbranch_vccz .LBB11_231
	s_barrier

; #define PG8_STAGE(bufoff, gbase, voff) do { _Pragma("unroll") for (int _i = 0; _i < 2; ++_i) \
;         __builtin_amdgcn_global_load_lds((const unsigned*)((const char*)(gbase) + (voff)[_i]), (PG8_LAS unsigned*)(lds + (bufoff) + ldsw + _i * 8192), 16, 0, 0); } while (0)
; #define PG8_LDA(dst, b, h) do { _Pragma("unroll") for (int m = 0; m < 4; ++m) _Pragma("unroll") for (int k = 0; k < 2; ++k) dst[m][k] = *(const PG8_LAS bf16x8*)(lds + PG8_SA(b, h) + aoff + m * 2048 + k * 1024); } while (0)
; #define PG8_LDB(dst, b, h) do { _Pragma("unroll") for (int n = 0; n < 2; ++n) _Pragma("unroll") for (int k = 0; k < 2; ++k) dst[n][k] = *(const PG8_LAS bf16x8*)(lds + PG8_SB(b, h) + boff + n * 2048 + k * 1024); } while (0)
; #define PG8_MMA(ai, bj, At, Bt) do { __builtin_amdgcn_s_setprio(1); _Pragma("unroll") for (int m = 0; m < 4; ++m) _Pragma("unroll") for (int n = 0; n < 2; ++n) _Pragma("unroll") for (int k = 0; k < 2; ++k) \
;         acc[ai][bj][m][n] = __builtin_amdgcn_mfma_f32_16x16x32_bf16(Bt[n][k], At[m][k], acc[ai][bj][m][n], 0, 0, 0); __builtin_amdgcn_s_setprio(0); } while (0)
; #define PG8_WAIT_V(n) asm volatile("s_waitcnt vmcnt(" #n ")" ::: "memory")
; #define PG8_WAIT_L(n) asm volatile("s_waitcnt lgkmcnt(" #n ")" ::: "memory")
; #define PG8_BAR __builtin_amdgcn_s_barrier()
; #define PG8_SCHED __builtin_amdgcn_sched_barrier(0)
; template <class Epi, class Sched, bool ALIGN_EPI = false, bool SP2 = false>
; __device__ __forceinline__ void gemm_phase(PG8_LAS unsigned char* lds, const Gemm g, const Sched& S, const Epi& E) {
;     ...
;             PG8_LDB(B0, 0, 0); PG8_LDB(B1, 0, 1); PG8_SCHED; PG8_LDA(At, 0, 0); PG8_STAGE(PG8_SA(1, 1), a1 + hstep, voffA);
;             PG8_WAIT_V(8); PG8_WAIT_L(0); PG8_BAR; PG8_MMA(0, 0, At, B0); PG8_MMA(0, 1, At, B1); PG8_BAR; PG8_SCHED;
;             PG8_LDA(At, 0, 1); PG8_STAGE(PG8_SB(0, 0), b2, voffB); PG8_STAGE(PG8_SB(0, 1), b2 + hstep, voffB); PG8_STAGE(PG8_SA(0, 0), a2, voffA);
.LBB11_456:
	s_add_u32 s18, s16, 0xfff80080
	s_addc_u32 s19, s17, -1
	s_add_i32 s49, 0, 0x10000
	s_cmp_eq_u32 s48, 28
	s_cselect_b32 s21, s11, s19
	s_cselect_b32 s20, s44, s18
	v_add_u32_e32 v144, s49, v147
	s_cselect_b32 s19, s9, s47
	s_cselect_b32 s18, s45, s46
	s_add_i32 s52, 0, 0x14000
	ds_read_b128 v[150:153], v144
	ds_read_b128 v[154:157], v144 offset:1024
	ds_read_b128 v[158:161], v144 offset:2048
	ds_read_b128 v[162:165], v144 offset:3072
	v_add_u32_e32 v144, s52, v147
	ds_read_b128 v[166:169], v144
	ds_read_b128 v[170:173], v144 offset:1024
	ds_read_b128 v[174:177], v144 offset:2048
	ds_read_b128 v[178:181], v144 offset:3072
	v_lshl_add_u64 v[144:145], s[16:17], 0, v[140:141]
	s_add_i32 m0, s29, 0xc000
	ds_read_b128 v[198:201], v149
	ds_read_b128 v[202:205], v149 offset:1024
	ds_read_b128 v[220:223], v149 offset:2048
	ds_read_b128 v[224:227], v149 offset:3072
	ds_read_b128 v[228:231], v149 offset:4096
	ds_read_b128 v[232:235], v149 offset:5120
	ds_read_b128 v[236:239], v149 offset:6144
	ds_read_b128 v[240:243], v149 offset:7168
	global_load_lds_dwordx4 v[144:145], off
	v_lshl_add_u64 v[144:145], s[16:17], 0, v[142:143]
	s_add_i32 m0, s29, 0xe000
	s_nop 0
	global_load_lds_dwordx4 v[144:145], off
	s_waitcnt vmcnt(8)
	s_waitcnt lgkmcnt(0)
	s_barrier
	s_setprio 1
	s_waitcnt lgkmcnt(0)
	v_mfma_f32_16x16x32_bf16 v[124:127], v[150:153], v[198:201], v[124:127]
	v_mfma_f32_16x16x32_bf16 v[108:111], v[150:153], v[220:223], v[108:111]
	v_mfma_f32_16x16x32_bf16 v[92:95], v[150:153], v[228:231], v[92:95]
	v_mfma_f32_16x16x32_bf16 v[76:79], v[150:153], v[236:239], v[76:79]
	v_mfma_f32_16x16x32_bf16 v[116:119], v[158:161], v[198:201], v[116:119]
	v_mfma_f32_16x16x32_bf16 v[100:103], v[158:161], v[220:223], v[100:103]
	v_mfma_f32_16x16x32_bf16 v[84:87], v[158:161], v[228:231], v[84:87]
	v_mfma_f32_16x16x32_bf16 v[68:71], v[158:161], v[236:239], v[68:71]
	v_mfma_f32_16x16x32_bf16 v[124:127], v[154:157], v[202:205], v[124:127]
	v_mfma_f32_16x16x32_bf16 v[108:111], v[154:157], v[224:227], v[108:111]
	v_mfma_f32_16x16x32_bf16 v[92:95], v[154:157], v[232:235], v[92:95]
	v_mfma_f32_16x16x32_bf16 v[76:79], v[154:157], v[240:243], v[76:79]
	v_mfma_f32_16x16x32_bf16 v[116:119], v[162:165], v[202:205], v[116:119]
	v_mfma_f32_16x16x32_bf16 v[100:103], v[162:165], v[224:227], v[100:103]
	v_mfma_f32_16x16x32_bf16 v[84:87], v[162:165], v[232:235], v[84:87]
	v_mfma_f32_16x16x32_bf16 v[68:71], v[162:165], v[240:243], v[68:71]
	s_setprio 0
	s_setprio 1
	v_mfma_f32_16x16x32_bf16 v[128:131], v[166:169], v[198:201], v[128:131]
	v_mfma_f32_16x16x32_bf16 v[112:115], v[166:169], v[220:223], v[112:115]
	v_mfma_f32_16x16x32_bf16 v[96:99], v[166:169], v[228:231], v[96:99]
	v_mfma_f32_16x16x32_bf16 v[80:83], v[166:169], v[236:239], v[80:83]
	v_mfma_f32_16x16x32_bf16 v[120:123], v[174:177], v[198:201], v[120:123]
	v_mfma_f32_16x16x32_bf16 v[104:107], v[174:177], v[220:223], v[104:107]
	v_mfma_f32_16x16x32_bf16 v[88:91], v[174:177], v[228:231], v[88:91]
	v_mfma_f32_16x16x32_bf16 v[72:75], v[174:177], v[236:239], v[72:75]
	v_mfma_f32_16x16x32_bf16 v[128:131], v[170:173], v[202:205], v[128:131]
	v_mfma_f32_16x16x32_bf16 v[112:115], v[170:173], v[224:227], v[112:115]
	v_mfma_f32_16x16x32_bf16 v[96:99], v[170:173], v[232:235], v[96:99]
	v_mfma_f32_16x16x32_bf16 v[80:83], v[170:173], v[240:243], v[80:83]
	v_mfma_f32_16x16x32_bf16 v[120:123], v[178:181], v[202:205], v[120:123]
	v_mfma_f32_16x16x32_bf16 v[104:107], v[178:181], v[224:227], v[104:107]
	v_mfma_f32_16x16x32_bf16 v[88:91], v[178:181], v[232:235], v[88:91]
	v_mfma_f32_16x16x32_bf16 v[72:75], v[178:181], v[240:243], v[72:75]
	s_setprio 0
	s_barrier
	s_add_i32 s49, s49, s27
	v_lshl_add_u64 v[144:145], s[18:19], 0, v[2:3]
	s_mov_b32 m0, s49
	ds_read_b128 v[198:201], v149 offset:16384
	ds_read_b128 v[202:205], v149 offset:17408
	ds_read_b128 v[220:223], v149 offset:18432
	ds_read_b128 v[224:227], v149 offset:19456
	ds_read_b128 v[228:231], v149 offset:20480
	ds_read_b128 v[232:235], v149 offset:21504
	ds_read_b128 v[236:239], v149 offset:22528
	ds_read_b128 v[240:243], v149 offset:23552
	global_load_lds_dwordx4 v[144:145], off
	s_add_i32 m0, s49, 0x2000
	s_add_u32 s50, s18, 0x80000
	v_lshl_add_u64 v[206:207], s[18:19], 0, v[132:133]
	s_addc_u32 s51, s19, 0
	s_add_i32 s49, s52, s27
	global_load_lds_dwordx4 v[206:207], off
	v_lshl_add_u64 v[244:245], s[50:51], 0, v[2:3]
	s_mov_b32 m0, s49
	v_lshl_add_u64 v[246:247], s[20:21], 0, v[134:135]
	global_load_lds_dwordx4 v[244:245], off
	v_lshl_add_u64 v[244:245], s[50:51], 0, v[132:133]
	s_add_i32 m0, s49, 0x2000
	s_nop 0
	global_load_lds_dwordx4 v[244:245], off
	v_lshl_add_u64 v[244:245], s[20:21], 0, v[136:137]
	s_mov_b32 m0, s29
	s_nop 0
	global_load_lds_dwordx4 v[244:245], off
	s_mov_b32 m0, s30
	s_nop 0
	global_load_lds_dwordx4 v[246:247], off
	s_waitcnt vmcnt(8)
	s_waitcnt lgkmcnt(0)
	s_barrier
; #define PG8_STAGE(bufoff, gbase, voff) do { _Pragma("unroll") for (int _i = 0; _i < 2; ++_i) \
;         __builtin_amdgcn_global_load_lds((const unsigned*)((const char*)(gbase) + (voff)[_i]), (PG8_LAS unsigned*)(lds + (bufoff) + ldsw + _i * 8192), 16, 0, 0); } while (0)
; #define PG8_LDA(dst, b, h) do { _Pragma("unroll") for (int m = 0; m < 4; ++m) _Pragma("unroll") for (int k = 0; k < 2; ++k) dst[m][k] = *(const PG8_LAS bf16x8*)(lds + PG8_SA(b, h) + aoff + m * 2048 + k * 1024); } while (0)
; #define PG8_LDB(dst, b, h) do { _Pragma("unroll") for (int n = 0; n < 2; ++n) _Pragma("unroll") for (int k = 0; k < 2; ++k) dst[n][k] = *(const PG8_LAS bf16x8*)(lds + PG8_SB(b, h) + boff + n * 2048 + k * 1024); } while (0)
; #define PG8_MMA(ai, bj, At, Bt) do { __builtin_amdgcn_s_setprio(1); _Pragma("unroll") for (int m = 0; m < 4; ++m) _Pragma("unroll") for (int n = 0; n < 2; ++n) _Pragma("unroll") for (int k = 0; k < 2; ++k) \
;         acc[ai][bj][m][n] = __builtin_amdgcn_mfma_f32_16x16x32_bf16(Bt[n][k], At[m][k], acc[ai][bj][m][n], 0, 0, 0); __builtin_amdgcn_s_setprio(0); } while (0)
; #define PG8_WAIT_V(n) asm volatile("s_waitcnt vmcnt(" #n ")" ::: "memory")
; #define PG8_WAIT_L(n) asm volatile("s_waitcnt lgkmcnt(" #n ")" ::: "memory")
; #define PG8_BAR __builtin_amdgcn_s_barrier()
; #define PG8_SCHED __builtin_amdgcn_sched_barrier(0)
; template <class Epi, class Sched, bool ALIGN_EPI = false, bool SP2 = false>
; __device__ __forceinline__ void gemm_phase(PG8_LAS unsigned char* lds, const Gemm g, const Sched& S, const Epi& E) {
;     ...
;             PG8_WAIT_V(8); PG8_WAIT_L(0); PG8_BAR; PG8_MMA(1, 0, At, B0); PG8_MMA(1, 1, At, B1); PG8_BAR; PG8_SCHED;
;             PG8_LDB(B0, 1, 0); PG8_LDB(B1, 1, 1); PG8_SCHED; PG8_LDA(At, 1, 0); PG8_STAGE(PG8_SA(0, 1), a2 + hstep, voffA);
;             PG8_WAIT_V(8); PG8_WAIT_L(0); PG8_BAR; PG8_MMA(0, 0, At, B0); PG8_MMA(0, 1, At, B1); PG8_BAR; PG8_SCHED;
	s_setprio 1
	s_waitcnt lgkmcnt(0)
	v_mfma_f32_16x16x32_bf16 v[60:63], v[150:153], v[198:201], v[60:63]
	v_mfma_f32_16x16x32_bf16 v[44:47], v[150:153], v[220:223], v[44:47]
	v_mfma_f32_16x16x32_bf16 v[28:31], v[150:153], v[228:231], v[28:31]
	v_mfma_f32_16x16x32_bf16 v[12:15], v[150:153], v[236:239], v[12:15]
	v_mfma_f32_16x16x32_bf16 v[52:55], v[158:161], v[198:201], v[52:55]
	v_mfma_f32_16x16x32_bf16 v[36:39], v[158:161], v[220:223], v[36:39]
	v_mfma_f32_16x16x32_bf16 v[20:23], v[158:161], v[228:231], v[20:23]
	v_mfma_f32_16x16x32_bf16 v[4:7], v[158:161], v[236:239], v[4:7]
	v_mfma_f32_16x16x32_bf16 v[60:63], v[154:157], v[202:205], v[60:63]
	v_mfma_f32_16x16x32_bf16 v[44:47], v[154:157], v[224:227], v[44:47]
	v_mfma_f32_16x16x32_bf16 v[28:31], v[154:157], v[232:235], v[28:31]
	v_mfma_f32_16x16x32_bf16 v[12:15], v[154:157], v[240:243], v[12:15]
	v_mfma_f32_16x16x32_bf16 v[52:55], v[162:165], v[202:205], v[52:55]
	v_mfma_f32_16x16x32_bf16 v[36:39], v[162:165], v[224:227], v[36:39]
	v_mfma_f32_16x16x32_bf16 v[20:23], v[162:165], v[232:235], v[20:23]
	v_mfma_f32_16x16x32_bf16 v[4:7], v[162:165], v[240:243], v[4:7]
	s_setprio 0
	s_setprio 1
	v_mfma_f32_16x16x32_bf16 v[64:67], v[166:169], v[198:201], v[64:67]
	v_mfma_f32_16x16x32_bf16 v[48:51], v[166:169], v[220:223], v[48:51]
	v_mfma_f32_16x16x32_bf16 v[32:35], v[166:169], v[228:231], v[32:35]
	v_mfma_f32_16x16x32_bf16 v[16:19], v[166:169], v[236:239], v[16:19]
	v_mfma_f32_16x16x32_bf16 v[56:59], v[174:177], v[198:201], v[56:59]
	v_mfma_f32_16x16x32_bf16 v[40:43], v[174:177], v[220:223], v[40:43]
	v_mfma_f32_16x16x32_bf16 v[24:27], v[174:177], v[228:231], v[24:27]
	v_mfma_f32_16x16x32_bf16 v[8:11], v[174:177], v[236:239], v[8:11]
	v_mfma_f32_16x16x32_bf16 v[64:67], v[170:173], v[202:205], v[64:67]
	v_mfma_f32_16x16x32_bf16 v[48:51], v[170:173], v[224:227], v[48:51]
	v_mfma_f32_16x16x32_bf16 v[32:35], v[170:173], v[232:235], v[32:35]
	v_mfma_f32_16x16x32_bf16 v[16:19], v[170:173], v[240:243], v[16:19]
	v_mfma_f32_16x16x32_bf16 v[56:59], v[178:181], v[202:205], v[56:59]
	v_mfma_f32_16x16x32_bf16 v[40:43], v[178:181], v[224:227], v[40:43]
	v_mfma_f32_16x16x32_bf16 v[24:27], v[178:181], v[232:235], v[24:27]
	v_mfma_f32_16x16x32_bf16 v[8:11], v[178:181], v[240:243], v[8:11]
	s_setprio 0
	s_barrier
	s_add_i32 s49, 0, 0x18000
	s_add_i32 s50, 0, 0x1c000
	v_add_u32_e32 v162, s49, v147
	v_add_u32_e32 v178, s50, v147
	ds_read_b128 v[150:153], v162
	ds_read_b128 v[154:157], v162 offset:1024
	ds_read_b128 v[158:161], v162 offset:2048
	ds_read_b128 v[162:165], v162 offset:3072
	ds_read_b128 v[166:169], v178
	ds_read_b128 v[170:173], v178 offset:1024
	ds_read_b128 v[174:177], v178 offset:2048
	ds_read_b128 v[178:181], v178 offset:3072
	s_add_u32 s20, s20, 0x80000
	s_addc_u32 s21, s21, 0
	s_mov_b32 m0, s33
	v_lshl_add_u64 v[196:197], s[20:21], 0, v[136:137]
	ds_read_b128 v[198:201], v149 offset:32768
	ds_read_b128 v[202:205], v149 offset:33792
	ds_read_b128 v[220:223], v149 offset:34816
	ds_read_b128 v[224:227], v149 offset:35840
	ds_read_b128 v[228:231], v149 offset:36864
	ds_read_b128 v[232:235], v149 offset:37888
	ds_read_b128 v[236:239], v149 offset:38912
	ds_read_b128 v[240:243], v149 offset:39936
	global_load_lds_dwordx4 v[196:197], off
	v_lshl_add_u64 v[196:197], s[20:21], 0, v[134:135]
	s_mov_b32 m0, s38
	s_nop 0
	global_load_lds_dwordx4 v[196:197], off
	s_waitcnt vmcnt(8)
	s_waitcnt lgkmcnt(0)
	s_barrier
	s_setprio 1
	s_waitcnt lgkmcnt(0)
	v_mfma_f32_16x16x32_bf16 v[124:127], v[150:153], v[198:201], v[124:127]
	v_mfma_f32_16x16x32_bf16 v[108:111], v[150:153], v[220:223], v[108:111]
	v_mfma_f32_16x16x32_bf16 v[92:95], v[150:153], v[228:231], v[92:95]
	v_mfma_f32_16x16x32_bf16 v[76:79], v[150:153], v[236:239], v[76:79]
	v_mfma_f32_16x16x32_bf16 v[116:119], v[158:161], v[198:201], v[116:119]
	v_mfma_f32_16x16x32_bf16 v[100:103], v[158:161], v[220:223], v[100:103]
	v_mfma_f32_16x16x32_bf16 v[84:87], v[158:161], v[228:231], v[84:87]
	v_mfma_f32_16x16x32_bf16 v[68:71], v[158:161], v[236:239], v[68:71]
	v_mfma_f32_16x16x32_bf16 v[124:127], v[154:157], v[202:205], v[124:127]
	v_mfma_f32_16x16x32_bf16 v[108:111], v[154:157], v[224:227], v[108:111]
	v_mfma_f32_16x16x32_bf16 v[92:95], v[154:157], v[232:235], v[92:95]
	v_mfma_f32_16x16x32_bf16 v[76:79], v[154:157], v[240:243], v[76:79]
	v_mfma_f32_16x16x32_bf16 v[116:119], v[162:165], v[202:205], v[116:119]
	v_mfma_f32_16x16x32_bf16 v[100:103], v[162:165], v[224:227], v[100:103]
	v_mfma_f32_16x16x32_bf16 v[84:87], v[162:165], v[232:235], v[84:87]
	v_mfma_f32_16x16x32_bf16 v[68:71], v[162:165], v[240:243], v[68:71]
	s_setprio 0
	s_setprio 1
	v_mfma_f32_16x16x32_bf16 v[128:131], v[166:169], v[198:201], v[128:131]
	v_mfma_f32_16x16x32_bf16 v[112:115], v[166:169], v[220:223], v[112:115]
	v_mfma_f32_16x16x32_bf16 v[96:99], v[166:169], v[228:231], v[96:99]
	v_mfma_f32_16x16x32_bf16 v[80:83], v[166:169], v[236:239], v[80:83]
	v_mfma_f32_16x16x32_bf16 v[120:123], v[174:177], v[198:201], v[120:123]
	v_mfma_f32_16x16x32_bf16 v[104:107], v[174:177], v[220:223], v[104:107]
	v_mfma_f32_16x16x32_bf16 v[88:91], v[174:177], v[228:231], v[88:91]
	v_mfma_f32_16x16x32_bf16 v[72:75], v[174:177], v[236:239], v[72:75]
	v_mfma_f32_16x16x32_bf16 v[128:131], v[170:173], v[202:205], v[128:131]
	v_mfma_f32_16x16x32_bf16 v[112:115], v[170:173], v[224:227], v[112:115]
	v_mfma_f32_16x16x32_bf16 v[96:99], v[170:173], v[232:235], v[96:99]
	v_mfma_f32_16x16x32_bf16 v[80:83], v[170:173], v[240:243], v[80:83]
	v_mfma_f32_16x16x32_bf16 v[120:123], v[178:181], v[202:205], v[120:123]
	v_mfma_f32_16x16x32_bf16 v[104:107], v[178:181], v[224:227], v[104:107]
	v_mfma_f32_16x16x32_bf16 v[88:91], v[178:181], v[232:235], v[88:91]
	v_mfma_f32_16x16x32_bf16 v[72:75], v[178:181], v[240:243], v[72:75]
	s_setprio 0
	s_barrier
; #define PG8_STAGE(bufoff, gbase, voff) do { _Pragma("unroll") for (int _i = 0; _i < 2; ++_i) \
;         __builtin_amdgcn_global_load_lds((const unsigned*)((const char*)(gbase) + (voff)[_i]), (PG8_LAS unsigned*)(lds + (bufoff) + ldsw + _i * 8192), 16, 0, 0); } while (0)
; #define PG8_LDA(dst, b, h) do { _Pragma("unroll") for (int m = 0; m < 4; ++m) _Pragma("unroll") for (int k = 0; k < 2; ++k) dst[m][k] = *(const PG8_LAS bf16x8*)(lds + PG8_SA(b, h) + aoff + m * 2048 + k * 1024); } while (0)
; #define PG8_MMA(ai, bj, At, Bt) do { __builtin_amdgcn_s_setprio(1); _Pragma("unroll") for (int m = 0; m < 4; ++m) _Pragma("unroll") for (int n = 0; n < 2; ++n) _Pragma("unroll") for (int k = 0; k < 2; ++k) \
;         acc[ai][bj][m][n] = __builtin_amdgcn_mfma_f32_16x16x32_bf16(Bt[n][k], At[m][k], acc[ai][bj][m][n], 0, 0, 0); __builtin_amdgcn_s_setprio(0); } while (0)
; #define PG8_WAIT_V(n) asm volatile("s_waitcnt vmcnt(" #n ")" ::: "memory")
; #define PG8_WAIT_L(n) asm volatile("s_waitcnt lgkmcnt(" #n ")" ::: "memory")
; #define PG8_BAR __builtin_amdgcn_s_barrier()
; #define PG8_SCHED __builtin_amdgcn_sched_barrier(0)
; template <class Epi, class Sched, bool ALIGN_EPI = false, bool SP2 = false>
; __device__ __forceinline__ void gemm_phase(PG8_LAS unsigned char* lds, const Gemm g, const Sched& S, const Epi& E) {
;     ...
;             PG8_LDA(At, 1, 1); PG8_STAGE(PG8_SB(1, 0), b3, voffB); PG8_STAGE(PG8_SB(1, 1), b3 + hstep, voffB); PG8_STAGE(PG8_SA(1, 0), a3, voffA);
;             PG8_WAIT_V(8); PG8_WAIT_L(0); PG8_BAR; PG8_MMA(1, 0, At, B0); PG8_MMA(1, 1, At, B1); PG8_BAR; PG8_SCHED;
	s_add_i32 s20, s49, s27
	v_lshl_add_u64 v[144:145], v[144:145], 0, s[34:35]
	s_mov_b32 m0, s20
	ds_read_b128 v[198:201], v149 offset:49152
	ds_read_b128 v[202:205], v149 offset:50176
	ds_read_b128 v[220:223], v149 offset:51200
	ds_read_b128 v[224:227], v149 offset:52224
	ds_read_b128 v[228:231], v149 offset:53248
	ds_read_b128 v[232:235], v149 offset:54272
	ds_read_b128 v[236:239], v149 offset:55296
	ds_read_b128 v[240:243], v149 offset:56320
	global_load_lds_dwordx4 v[144:145], off
	s_add_i32 m0, s20, 0x2000
	s_add_u32 s18, s18, 0x80080
	v_lshl_add_u64 v[144:145], v[206:207], 0, s[34:35]
	s_addc_u32 s19, s19, 0
	s_add_i32 s20, s50, s27
	global_load_lds_dwordx4 v[144:145], off
	v_lshl_add_u64 v[144:145], s[18:19], 0, v[2:3]
	s_mov_b32 m0, s20
	s_nop 0
	global_load_lds_dwordx4 v[144:145], off
	v_lshl_add_u64 v[144:145], s[18:19], 0, v[132:133]
	s_add_i32 m0, s20, 0x2000
	s_nop 0
	global_load_lds_dwordx4 v[144:145], off
	v_lshl_add_u64 v[144:145], v[244:245], 0, s[34:35]
	s_mov_b32 m0, s39
	s_nop 0
	global_load_lds_dwordx4 v[144:145], off
	v_lshl_add_u64 v[144:145], v[246:247], 0, s[34:35]
	s_mov_b32 m0, s40
	s_nop 0
	global_load_lds_dwordx4 v[144:145], off
	s_waitcnt vmcnt(8)
	s_waitcnt lgkmcnt(0)
	s_barrier
	s_setprio 1
	s_waitcnt lgkmcnt(0)
	v_mfma_f32_16x16x32_bf16 v[60:63], v[150:153], v[198:201], v[60:63]
	v_mfma_f32_16x16x32_bf16 v[44:47], v[150:153], v[220:223], v[44:47]
	v_mfma_f32_16x16x32_bf16 v[28:31], v[150:153], v[228:231], v[28:31]
	v_mfma_f32_16x16x32_bf16 v[12:15], v[150:153], v[236:239], v[12:15]
	v_mfma_f32_16x16x32_bf16 v[52:55], v[158:161], v[198:201], v[52:55]
	v_mfma_f32_16x16x32_bf16 v[36:39], v[158:161], v[220:223], v[36:39]
	v_mfma_f32_16x16x32_bf16 v[20:23], v[158:161], v[228:231], v[20:23]
	v_mfma_f32_16x16x32_bf16 v[4:7], v[158:161], v[236:239], v[4:7]
	v_mfma_f32_16x16x32_bf16 v[60:63], v[154:157], v[202:205], v[60:63]
	v_mfma_f32_16x16x32_bf16 v[44:47], v[154:157], v[224:227], v[44:47]
	v_mfma_f32_16x16x32_bf16 v[28:31], v[154:157], v[232:235], v[28:31]
	v_mfma_f32_16x16x32_bf16 v[12:15], v[154:157], v[240:243], v[12:15]
	v_mfma_f32_16x16x32_bf16 v[52:55], v[162:165], v[202:205], v[52:55]
	v_mfma_f32_16x16x32_bf16 v[36:39], v[162:165], v[224:227], v[36:39]
	v_mfma_f32_16x16x32_bf16 v[20:23], v[162:165], v[232:235], v[20:23]
	v_mfma_f32_16x16x32_bf16 v[4:7], v[162:165], v[240:243], v[4:7]
	s_setprio 0
	s_setprio 1
	v_mfma_f32_16x16x32_bf16 v[64:67], v[166:169], v[198:201], v[64:67]
	v_mfma_f32_16x16x32_bf16 v[48:51], v[166:169], v[220:223], v[48:51]
	v_mfma_f32_16x16x32_bf16 v[32:35], v[166:169], v[228:231], v[32:35]
	v_mfma_f32_16x16x32_bf16 v[16:19], v[166:169], v[236:239], v[16:19]
	v_mfma_f32_16x16x32_bf16 v[56:59], v[174:177], v[198:201], v[56:59]
	v_mfma_f32_16x16x32_bf16 v[40:43], v[174:177], v[220:223], v[40:43]
	v_mfma_f32_16x16x32_bf16 v[24:27], v[174:177], v[228:231], v[24:27]
	v_mfma_f32_16x16x32_bf16 v[8:11], v[174:177], v[236:239], v[8:11]
	v_mfma_f32_16x16x32_bf16 v[64:67], v[170:173], v[202:205], v[64:67]
	v_mfma_f32_16x16x32_bf16 v[48:51], v[170:173], v[224:227], v[48:51]
	v_mfma_f32_16x16x32_bf16 v[32:35], v[170:173], v[232:235], v[32:35]
	v_mfma_f32_16x16x32_bf16 v[16:19], v[170:173], v[240:243], v[16:19]
	v_mfma_f32_16x16x32_bf16 v[56:59], v[178:181], v[202:205], v[56:59]
	v_mfma_f32_16x16x32_bf16 v[40:43], v[178:181], v[224:227], v[40:43]
	v_mfma_f32_16x16x32_bf16 v[24:27], v[178:181], v[232:235], v[24:27]
	v_mfma_f32_16x16x32_bf16 v[8:11], v[178:181], v[240:243], v[8:11]
	s_setprio 0
	s_barrier
	s_add_i32 s48, s48, 2
	s_add_u32 s16, s16, 0x100
	s_addc_u32 s17, s17, 0
	s_add_u32 s46, s46, 0x100
	s_addc_u32 s47, s47, 0
	s_cmp_gt_u32 s48, 29
	s_cbranch_scc0 .LBB11_456
	s_and_b64 vcc, exec, s[6:7]
	s_cbranch_vccz .LBB11_459
	s_barrier

; #define PG8_STAGE(bufoff, gbase, voff) do { _Pragma("unroll") for (int _i = 0; _i < 2; ++_i) \
;         __builtin_amdgcn_global_load_lds((const unsigned*)((const char*)(gbase) + (voff)[_i]), (PG8_LAS unsigned*)(lds + (bufoff) + ldsw + _i * 8192), 16, 0, 0); } while (0)
; #define PG8_LDA(dst, b, h) do { _Pragma("unroll") for (int m = 0; m < 4; ++m) _Pragma("unroll") for (int k = 0; k < 2; ++k) dst[m][k] = *(const PG8_LAS bf16x8*)(lds + PG8_SA(b, h) + aoff + m * 2048 + k * 1024); } while (0)
; #define PG8_LDB(dst, b, h) do { _Pragma("unroll") for (int n = 0; n < 2; ++n) _Pragma("unroll") for (int k = 0; k < 2; ++k) dst[n][k] = *(const PG8_LAS bf16x8*)(lds + PG8_SB(b, h) + boff + n * 2048 + k * 1024); } while (0)
; #define PG8_MMA(ai, bj, At, Bt) do { __builtin_amdgcn_s_setprio(1); _Pragma("unroll") for (int m = 0; m < 4; ++m) _Pragma("unroll") for (int n = 0; n < 2; ++n) _Pragma("unroll") for (int k = 0; k < 2; ++k) \
;         acc[ai][bj][m][n] = __builtin_amdgcn_mfma_f32_16x16x32_bf16(Bt[n][k], At[m][k], acc[ai][bj][m][n], 0, 0, 0); __builtin_amdgcn_s_setprio(0); } while (0)
; #define PG8_WAIT_V(n) asm volatile("s_waitcnt vmcnt(" #n ")" ::: "memory")
; #define PG8_WAIT_L(n) asm volatile("s_waitcnt lgkmcnt(" #n ")" ::: "memory")
; #define PG8_BAR __builtin_amdgcn_s_barrier()
; #define PG8_SCHED __builtin_amdgcn_sched_barrier(0)
; template <class Epi, class Sched, bool ALIGN_EPI = false, bool SP2 = false>
; __device__ __forceinline__ void gemm_phase(PG8_LAS unsigned char* lds, const Gemm g, const Sched& S, const Epi& E) {
;     ...
;             PG8_LDB(B0, 0, 0); PG8_LDB(B1, 0, 1); PG8_SCHED; PG8_LDA(At, 0, 0); PG8_STAGE(PG8_SA(1, 1), a1 + hstep, voffA);
;             PG8_WAIT_V(8); PG8_WAIT_L(0); PG8_BAR; PG8_MMA(0, 0, At, B0); PG8_MMA(0, 1, At, B1); PG8_BAR; PG8_SCHED;
;             PG8_LDA(At, 0, 1); PG8_STAGE(PG8_SB(0, 0), b2, voffB); PG8_STAGE(PG8_SB(0, 1), b2 + hstep, voffB); PG8_STAGE(PG8_SA(0, 0), a2, voffA);
.LBB11_638:
	s_add_u32 s20, s18, 0xfff80080
	s_addc_u32 s21, s19, -1
	s_add_i32 s49, 0, 0x10000
	s_cmp_eq_u32 s48, 28
	s_cselect_b32 s23, s13, s21
	s_cselect_b32 s22, s44, s20
	v_add_u32_e32 v144, s49, v147
	s_cselect_b32 s21, s11, s47
	s_cselect_b32 s20, s45, s46
	s_add_i32 s52, 0, 0x14000
	ds_read_b128 v[150:153], v144
	ds_read_b128 v[154:157], v144 offset:1024
	ds_read_b128 v[158:161], v144 offset:2048
	ds_read_b128 v[162:165], v144 offset:3072
	v_add_u32_e32 v144, s52, v147
	ds_read_b128 v[166:169], v144
	ds_read_b128 v[170:173], v144 offset:1024
	ds_read_b128 v[174:177], v144 offset:2048
	ds_read_b128 v[178:181], v144 offset:3072
	v_lshl_add_u64 v[144:145], s[18:19], 0, v[140:141]
	s_add_i32 m0, s33, 0xc000
	ds_read_b128 v[198:201], v149
	ds_read_b128 v[202:205], v149 offset:1024
	ds_read_b128 v[220:223], v149 offset:2048
	ds_read_b128 v[224:227], v149 offset:3072
	ds_read_b128 v[228:231], v149 offset:4096
	ds_read_b128 v[232:235], v149 offset:5120
	ds_read_b128 v[236:239], v149 offset:6144
	ds_read_b128 v[240:243], v149 offset:7168
	global_load_lds_dwordx4 v[144:145], off
	v_lshl_add_u64 v[144:145], s[18:19], 0, v[142:143]
	s_add_i32 m0, s33, 0xe000
	s_nop 0
	global_load_lds_dwordx4 v[144:145], off
	s_waitcnt vmcnt(8)
	s_waitcnt lgkmcnt(0)
	s_barrier
	s_setprio 1
	s_waitcnt lgkmcnt(0)
	v_mfma_f32_16x16x32_bf16 v[128:131], v[150:153], v[198:201], v[128:131]
	v_mfma_f32_16x16x32_bf16 v[120:123], v[150:153], v[220:223], v[120:123]
	v_mfma_f32_16x16x32_bf16 v[104:107], v[150:153], v[228:231], v[104:107]
	v_mfma_f32_16x16x32_bf16 v[88:91], v[150:153], v[236:239], v[88:91]
	v_mfma_f32_16x16x32_bf16 v[124:127], v[158:161], v[198:201], v[124:127]
	v_mfma_f32_16x16x32_bf16 v[112:115], v[158:161], v[220:223], v[112:115]
	v_mfma_f32_16x16x32_bf16 v[96:99], v[158:161], v[228:231], v[96:99]
	v_mfma_f32_16x16x32_bf16 v[80:83], v[158:161], v[236:239], v[80:83]
	v_mfma_f32_16x16x32_bf16 v[128:131], v[154:157], v[202:205], v[128:131]
	v_mfma_f32_16x16x32_bf16 v[120:123], v[154:157], v[224:227], v[120:123]
	v_mfma_f32_16x16x32_bf16 v[104:107], v[154:157], v[232:235], v[104:107]
	v_mfma_f32_16x16x32_bf16 v[88:91], v[154:157], v[240:243], v[88:91]
	v_mfma_f32_16x16x32_bf16 v[124:127], v[162:165], v[202:205], v[124:127]
	v_mfma_f32_16x16x32_bf16 v[112:115], v[162:165], v[224:227], v[112:115]
	v_mfma_f32_16x16x32_bf16 v[96:99], v[162:165], v[232:235], v[96:99]
	v_mfma_f32_16x16x32_bf16 v[80:83], v[162:165], v[240:243], v[80:83]
	s_setprio 0
	s_setprio 1
	v_mfma_f32_16x16x32_bf16 v[116:119], v[166:169], v[198:201], v[116:119]
	v_mfma_f32_16x16x32_bf16 v[100:103], v[166:169], v[220:223], v[100:103]
	v_mfma_f32_16x16x32_bf16 v[84:87], v[166:169], v[228:231], v[84:87]
	v_mfma_f32_16x16x32_bf16 v[72:75], v[166:169], v[236:239], v[72:75]
	v_mfma_f32_16x16x32_bf16 v[108:111], v[174:177], v[198:201], v[108:111]
	v_mfma_f32_16x16x32_bf16 v[92:95], v[174:177], v[220:223], v[92:95]
	v_mfma_f32_16x16x32_bf16 v[76:79], v[174:177], v[228:231], v[76:79]
	v_mfma_f32_16x16x32_bf16 v[68:71], v[174:177], v[236:239], v[68:71]
	v_mfma_f32_16x16x32_bf16 v[116:119], v[170:173], v[202:205], v[116:119]
	v_mfma_f32_16x16x32_bf16 v[100:103], v[170:173], v[224:227], v[100:103]
	v_mfma_f32_16x16x32_bf16 v[84:87], v[170:173], v[232:235], v[84:87]
	v_mfma_f32_16x16x32_bf16 v[72:75], v[170:173], v[240:243], v[72:75]
	v_mfma_f32_16x16x32_bf16 v[108:111], v[178:181], v[202:205], v[108:111]
	v_mfma_f32_16x16x32_bf16 v[92:95], v[178:181], v[224:227], v[92:95]
	v_mfma_f32_16x16x32_bf16 v[76:79], v[178:181], v[232:235], v[76:79]
	v_mfma_f32_16x16x32_bf16 v[68:71], v[178:181], v[240:243], v[68:71]
	s_setprio 0
	s_barrier
	s_add_i32 s49, s49, s30
	v_lshl_add_u64 v[144:145], s[20:21], 0, v[2:3]
	s_mov_b32 m0, s49
	ds_read_b128 v[198:201], v149 offset:16384
	ds_read_b128 v[202:205], v149 offset:17408
	ds_read_b128 v[220:223], v149 offset:18432
	ds_read_b128 v[224:227], v149 offset:19456
	ds_read_b128 v[228:231], v149 offset:20480
	ds_read_b128 v[232:235], v149 offset:21504
	ds_read_b128 v[236:239], v149 offset:22528
	ds_read_b128 v[240:243], v149 offset:23552
	global_load_lds_dwordx4 v[144:145], off
	s_add_i32 m0, s49, 0x2000
	s_add_u32 s50, s20, 0x80000
	v_lshl_add_u64 v[184:185], s[20:21], 0, v[132:133]
	s_addc_u32 s51, s21, 0
	s_add_i32 s49, s52, s30
	global_load_lds_dwordx4 v[184:185], off
	v_lshl_add_u64 v[186:187], s[50:51], 0, v[2:3]
	s_mov_b32 m0, s49
	v_lshl_add_u64 v[196:197], s[22:23], 0, v[134:135]
	global_load_lds_dwordx4 v[186:187], off
	v_lshl_add_u64 v[186:187], s[50:51], 0, v[132:133]
	s_add_i32 m0, s49, 0x2000
	s_nop 0
	global_load_lds_dwordx4 v[186:187], off
	v_lshl_add_u64 v[186:187], s[22:23], 0, v[136:137]
	s_mov_b32 m0, s33
	s_nop 0
	global_load_lds_dwordx4 v[186:187], off
	s_mov_b32 m0, s36
	s_nop 0
	global_load_lds_dwordx4 v[196:197], off
	s_waitcnt vmcnt(8)
	s_waitcnt lgkmcnt(0)
	s_barrier
; #define PG8_STAGE(bufoff, gbase, voff) do { _Pragma("unroll") for (int _i = 0; _i < 2; ++_i) \
;         __builtin_amdgcn_global_load_lds((const unsigned*)((const char*)(gbase) + (voff)[_i]), (PG8_LAS unsigned*)(lds + (bufoff) + ldsw + _i * 8192), 16, 0, 0); } while (0)
; #define PG8_LDA(dst, b, h) do { _Pragma("unroll") for (int m = 0; m < 4; ++m) _Pragma("unroll") for (int k = 0; k < 2; ++k) dst[m][k] = *(const PG8_LAS bf16x8*)(lds + PG8_SA(b, h) + aoff + m * 2048 + k * 1024); } while (0)
; #define PG8_LDB(dst, b, h) do { _Pragma("unroll") for (int n = 0; n < 2; ++n) _Pragma("unroll") for (int k = 0; k < 2; ++k) dst[n][k] = *(const PG8_LAS bf16x8*)(lds + PG8_SB(b, h) + boff + n * 2048 + k * 1024); } while (0)
; #define PG8_MMA(ai, bj, At, Bt) do { __builtin_amdgcn_s_setprio(1); _Pragma("unroll") for (int m = 0; m < 4; ++m) _Pragma("unroll") for (int n = 0; n < 2; ++n) _Pragma("unroll") for (int k = 0; k < 2; ++k) \
;         acc[ai][bj][m][n] = __builtin_amdgcn_mfma_f32_16x16x32_bf16(Bt[n][k], At[m][k], acc[ai][bj][m][n], 0, 0, 0); __builtin_amdgcn_s_setprio(0); } while (0)
; #define PG8_WAIT_V(n) asm volatile("s_waitcnt vmcnt(" #n ")" ::: "memory")
; #define PG8_WAIT_L(n) asm volatile("s_waitcnt lgkmcnt(" #n ")" ::: "memory")
; #define PG8_BAR __builtin_amdgcn_s_barrier()
; #define PG8_SCHED __builtin_amdgcn_sched_barrier(0)
; template <class Epi, class Sched, bool ALIGN_EPI = false, bool SP2 = false>
; __device__ __forceinline__ void gemm_phase(PG8_LAS unsigned char* lds, const Gemm g, const Sched& S, const Epi& E) {
;     ...
;             PG8_WAIT_V(8); PG8_WAIT_L(0); PG8_BAR; PG8_MMA(1, 0, At, B0); PG8_MMA(1, 1, At, B1); PG8_BAR; PG8_SCHED;
;             PG8_LDB(B0, 1, 0); PG8_LDB(B1, 1, 1); PG8_SCHED; PG8_LDA(At, 1, 0); PG8_STAGE(PG8_SA(0, 1), a2 + hstep, voffA);
;             PG8_WAIT_V(8); PG8_WAIT_L(0); PG8_BAR; PG8_MMA(0, 0, At, B0); PG8_MMA(0, 1, At, B1); PG8_BAR; PG8_SCHED;
	s_setprio 1
	s_waitcnt lgkmcnt(0)
	v_mfma_f32_16x16x32_bf16 v[64:67], v[150:153], v[198:201], v[64:67]
	v_mfma_f32_16x16x32_bf16 v[56:59], v[150:153], v[220:223], v[56:59]
	v_mfma_f32_16x16x32_bf16 v[40:43], v[150:153], v[228:231], v[40:43]
	v_mfma_f32_16x16x32_bf16 v[24:27], v[150:153], v[236:239], v[24:27]
	v_mfma_f32_16x16x32_bf16 v[60:63], v[158:161], v[198:201], v[60:63]
	v_mfma_f32_16x16x32_bf16 v[48:51], v[158:161], v[220:223], v[48:51]
	v_mfma_f32_16x16x32_bf16 v[32:35], v[158:161], v[228:231], v[32:35]
	v_mfma_f32_16x16x32_bf16 v[16:19], v[158:161], v[236:239], v[16:19]
	v_mfma_f32_16x16x32_bf16 v[64:67], v[154:157], v[202:205], v[64:67]
	v_mfma_f32_16x16x32_bf16 v[56:59], v[154:157], v[224:227], v[56:59]
	v_mfma_f32_16x16x32_bf16 v[40:43], v[154:157], v[232:235], v[40:43]
	v_mfma_f32_16x16x32_bf16 v[24:27], v[154:157], v[240:243], v[24:27]
	v_mfma_f32_16x16x32_bf16 v[60:63], v[162:165], v[202:205], v[60:63]
	v_mfma_f32_16x16x32_bf16 v[48:51], v[162:165], v[224:227], v[48:51]
	v_mfma_f32_16x16x32_bf16 v[32:35], v[162:165], v[232:235], v[32:35]
	v_mfma_f32_16x16x32_bf16 v[16:19], v[162:165], v[240:243], v[16:19]
	s_setprio 0
	s_setprio 1
	v_mfma_f32_16x16x32_bf16 v[52:55], v[166:169], v[198:201], v[52:55]
	v_mfma_f32_16x16x32_bf16 v[36:39], v[166:169], v[220:223], v[36:39]
	v_mfma_f32_16x16x32_bf16 v[20:23], v[166:169], v[228:231], v[20:23]
	v_mfma_f32_16x16x32_bf16 v[8:11], v[166:169], v[236:239], v[8:11]
	v_mfma_f32_16x16x32_bf16 v[44:47], v[174:177], v[198:201], v[44:47]
	v_mfma_f32_16x16x32_bf16 v[28:31], v[174:177], v[220:223], v[28:31]
	v_mfma_f32_16x16x32_bf16 v[12:15], v[174:177], v[228:231], v[12:15]
	v_mfma_f32_16x16x32_bf16 v[4:7], v[174:177], v[236:239], v[4:7]
	v_mfma_f32_16x16x32_bf16 v[52:55], v[170:173], v[202:205], v[52:55]
	v_mfma_f32_16x16x32_bf16 v[36:39], v[170:173], v[224:227], v[36:39]
	v_mfma_f32_16x16x32_bf16 v[20:23], v[170:173], v[232:235], v[20:23]
	v_mfma_f32_16x16x32_bf16 v[8:11], v[170:173], v[240:243], v[8:11]
	v_mfma_f32_16x16x32_bf16 v[44:47], v[178:181], v[202:205], v[44:47]
	v_mfma_f32_16x16x32_bf16 v[28:31], v[178:181], v[224:227], v[28:31]
	v_mfma_f32_16x16x32_bf16 v[12:15], v[178:181], v[232:235], v[12:15]
	v_mfma_f32_16x16x32_bf16 v[4:7], v[178:181], v[240:243], v[4:7]
	s_setprio 0
	s_barrier
	s_add_i32 s49, 0, 0x18000
	s_add_i32 s50, 0, 0x1c000
	v_add_u32_e32 v162, s49, v147
	v_add_u32_e32 v178, s50, v147
	ds_read_b128 v[150:153], v162
	ds_read_b128 v[154:157], v162 offset:1024
	ds_read_b128 v[158:161], v162 offset:2048
	ds_read_b128 v[162:165], v162 offset:3072
	ds_read_b128 v[166:169], v178
	ds_read_b128 v[170:173], v178 offset:1024
	ds_read_b128 v[174:177], v178 offset:2048
	ds_read_b128 v[178:181], v178 offset:3072
	s_add_u32 s22, s22, 0x80000
	s_addc_u32 s23, s23, 0
	s_mov_b32 m0, s37
	v_lshl_add_u64 v[206:207], s[22:23], 0, v[136:137]
	ds_read_b128 v[198:201], v149 offset:32768
	ds_read_b128 v[202:205], v149 offset:33792
	ds_read_b128 v[220:223], v149 offset:34816
	ds_read_b128 v[224:227], v149 offset:35840
	ds_read_b128 v[228:231], v149 offset:36864
	ds_read_b128 v[232:235], v149 offset:37888
	ds_read_b128 v[236:239], v149 offset:38912
	ds_read_b128 v[240:243], v149 offset:39936
	global_load_lds_dwordx4 v[206:207], off
	v_lshl_add_u64 v[206:207], s[22:23], 0, v[134:135]
	s_mov_b32 m0, s38
	s_nop 0
	global_load_lds_dwordx4 v[206:207], off
	s_waitcnt vmcnt(8)
	s_waitcnt lgkmcnt(0)
	s_barrier
	s_setprio 1
	s_waitcnt lgkmcnt(0)
	v_mfma_f32_16x16x32_bf16 v[128:131], v[150:153], v[198:201], v[128:131]
	v_mfma_f32_16x16x32_bf16 v[120:123], v[150:153], v[220:223], v[120:123]
	v_mfma_f32_16x16x32_bf16 v[104:107], v[150:153], v[228:231], v[104:107]
	v_mfma_f32_16x16x32_bf16 v[88:91], v[150:153], v[236:239], v[88:91]
	v_mfma_f32_16x16x32_bf16 v[124:127], v[158:161], v[198:201], v[124:127]
	v_mfma_f32_16x16x32_bf16 v[112:115], v[158:161], v[220:223], v[112:115]
	v_mfma_f32_16x16x32_bf16 v[96:99], v[158:161], v[228:231], v[96:99]
	v_mfma_f32_16x16x32_bf16 v[80:83], v[158:161], v[236:239], v[80:83]
	v_mfma_f32_16x16x32_bf16 v[128:131], v[154:157], v[202:205], v[128:131]
	v_mfma_f32_16x16x32_bf16 v[120:123], v[154:157], v[224:227], v[120:123]
	v_mfma_f32_16x16x32_bf16 v[104:107], v[154:157], v[232:235], v[104:107]
	v_mfma_f32_16x16x32_bf16 v[88:91], v[154:157], v[240:243], v[88:91]
	v_mfma_f32_16x16x32_bf16 v[124:127], v[162:165], v[202:205], v[124:127]
	v_mfma_f32_16x16x32_bf16 v[112:115], v[162:165], v[224:227], v[112:115]
	v_mfma_f32_16x16x32_bf16 v[96:99], v[162:165], v[232:235], v[96:99]
	v_mfma_f32_16x16x32_bf16 v[80:83], v[162:165], v[240:243], v[80:83]
	s_setprio 0
	s_setprio 1
	v_mfma_f32_16x16x32_bf16 v[116:119], v[166:169], v[198:201], v[116:119]
	v_mfma_f32_16x16x32_bf16 v[100:103], v[166:169], v[220:223], v[100:103]
	v_mfma_f32_16x16x32_bf16 v[84:87], v[166:169], v[228:231], v[84:87]
	v_mfma_f32_16x16x32_bf16 v[72:75], v[166:169], v[236:239], v[72:75]
	v_mfma_f32_16x16x32_bf16 v[108:111], v[174:177], v[198:201], v[108:111]
	v_mfma_f32_16x16x32_bf16 v[92:95], v[174:177], v[220:223], v[92:95]
	v_mfma_f32_16x16x32_bf16 v[76:79], v[174:177], v[228:231], v[76:79]
	v_mfma_f32_16x16x32_bf16 v[68:71], v[174:177], v[236:239], v[68:71]
	v_mfma_f32_16x16x32_bf16 v[116:119], v[170:173], v[202:205], v[116:119]
	v_mfma_f32_16x16x32_bf16 v[100:103], v[170:173], v[224:227], v[100:103]
	v_mfma_f32_16x16x32_bf16 v[84:87], v[170:173], v[232:235], v[84:87]
	v_mfma_f32_16x16x32_bf16 v[72:75], v[170:173], v[240:243], v[72:75]
	v_mfma_f32_16x16x32_bf16 v[108:111], v[178:181], v[202:205], v[108:111]
	v_mfma_f32_16x16x32_bf16 v[92:95], v[178:181], v[224:227], v[92:95]
	v_mfma_f32_16x16x32_bf16 v[76:79], v[178:181], v[232:235], v[76:79]
	v_mfma_f32_16x16x32_bf16 v[68:71], v[178:181], v[240:243], v[68:71]
	s_setprio 0
	s_barrier
; #define PG8_STAGE(bufoff, gbase, voff) do { _Pragma("unroll") for (int _i = 0; _i < 2; ++_i) \
;         __builtin_amdgcn_global_load_lds((const unsigned*)((const char*)(gbase) + (voff)[_i]), (PG8_LAS unsigned*)(lds + (bufoff) + ldsw + _i * 8192), 16, 0, 0); } while (0)
; #define PG8_LDA(dst, b, h) do { _Pragma("unroll") for (int m = 0; m < 4; ++m) _Pragma("unroll") for (int k = 0; k < 2; ++k) dst[m][k] = *(const PG8_LAS bf16x8*)(lds + PG8_SA(b, h) + aoff + m * 2048 + k * 1024); } while (0)
; #define PG8_MMA(ai, bj, At, Bt) do { __builtin_amdgcn_s_setprio(1); _Pragma("unroll") for (int m = 0; m < 4; ++m) _Pragma("unroll") for (int n = 0; n < 2; ++n) _Pragma("unroll") for (int k = 0; k < 2; ++k) \
;         acc[ai][bj][m][n] = __builtin_amdgcn_mfma_f32_16x16x32_bf16(Bt[n][k], At[m][k], acc[ai][bj][m][n], 0, 0, 0); __builtin_amdgcn_s_setprio(0); } while (0)
; #define PG8_WAIT_V(n) asm volatile("s_waitcnt vmcnt(" #n ")" ::: "memory")
; #define PG8_WAIT_L(n) asm volatile("s_waitcnt lgkmcnt(" #n ")" ::: "memory")
; #define PG8_BAR __builtin_amdgcn_s_barrier()
; #define PG8_SCHED __builtin_amdgcn_sched_barrier(0)
; template <class Epi, class Sched, bool ALIGN_EPI = false, bool SP2 = false>
; __device__ __forceinline__ void gemm_phase(PG8_LAS unsigned char* lds, const Gemm g, const Sched& S, const Epi& E) {
;     ...
;             PG8_LDA(At, 1, 1); PG8_STAGE(PG8_SB(1, 0), b3, voffB); PG8_STAGE(PG8_SB(1, 1), b3 + hstep, voffB); PG8_STAGE(PG8_SA(1, 0), a3, voffA);
;             PG8_WAIT_V(8); PG8_WAIT_L(0); PG8_BAR; PG8_MMA(1, 0, At, B0); PG8_MMA(1, 1, At, B1); PG8_BAR; PG8_SCHED;
	s_add_i32 s22, s49, s30
	v_lshl_add_u64 v[144:145], v[144:145], 0, s[34:35]
	s_mov_b32 m0, s22
	ds_read_b128 v[198:201], v149 offset:49152
	ds_read_b128 v[202:205], v149 offset:50176
	ds_read_b128 v[220:223], v149 offset:51200
	ds_read_b128 v[224:227], v149 offset:52224
	ds_read_b128 v[228:231], v149 offset:53248
	ds_read_b128 v[232:235], v149 offset:54272
	ds_read_b128 v[236:239], v149 offset:55296
	ds_read_b128 v[240:243], v149 offset:56320
	global_load_lds_dwordx4 v[144:145], off
	s_add_i32 m0, s22, 0x2000
	s_add_u32 s20, s20, 0x80080
	v_lshl_add_u64 v[144:145], v[184:185], 0, s[34:35]
	s_addc_u32 s21, s21, 0
	s_add_i32 s22, s50, s30
	global_load_lds_dwordx4 v[144:145], off
	v_lshl_add_u64 v[144:145], s[20:21], 0, v[2:3]
	s_mov_b32 m0, s22
	s_nop 0
	global_load_lds_dwordx4 v[144:145], off
	v_lshl_add_u64 v[144:145], s[20:21], 0, v[132:133]
	s_add_i32 m0, s22, 0x2000
	s_nop 0
	global_load_lds_dwordx4 v[144:145], off
	v_lshl_add_u64 v[144:145], v[186:187], 0, s[34:35]
	s_mov_b32 m0, s39
	s_nop 0
	global_load_lds_dwordx4 v[144:145], off
	v_lshl_add_u64 v[144:145], v[196:197], 0, s[34:35]
	s_mov_b32 m0, s40
	s_nop 0
	global_load_lds_dwordx4 v[144:145], off
	s_waitcnt vmcnt(8)
	s_waitcnt lgkmcnt(0)
	s_barrier
	s_setprio 1
	s_waitcnt lgkmcnt(0)
	v_mfma_f32_16x16x32_bf16 v[64:67], v[150:153], v[198:201], v[64:67]
	v_mfma_f32_16x16x32_bf16 v[56:59], v[150:153], v[220:223], v[56:59]
	v_mfma_f32_16x16x32_bf16 v[40:43], v[150:153], v[228:231], v[40:43]
	v_mfma_f32_16x16x32_bf16 v[24:27], v[150:153], v[236:239], v[24:27]
	v_mfma_f32_16x16x32_bf16 v[60:63], v[158:161], v[198:201], v[60:63]
	v_mfma_f32_16x16x32_bf16 v[48:51], v[158:161], v[220:223], v[48:51]
	v_mfma_f32_16x16x32_bf16 v[32:35], v[158:161], v[228:231], v[32:35]
	v_mfma_f32_16x16x32_bf16 v[16:19], v[158:161], v[236:239], v[16:19]
	v_mfma_f32_16x16x32_bf16 v[64:67], v[154:157], v[202:205], v[64:67]
	v_mfma_f32_16x16x32_bf16 v[56:59], v[154:157], v[224:227], v[56:59]
	v_mfma_f32_16x16x32_bf16 v[40:43], v[154:157], v[232:235], v[40:43]
	v_mfma_f32_16x16x32_bf16 v[24:27], v[154:157], v[240:243], v[24:27]
	v_mfma_f32_16x16x32_bf16 v[60:63], v[162:165], v[202:205], v[60:63]
	v_mfma_f32_16x16x32_bf16 v[48:51], v[162:165], v[224:227], v[48:51]
	v_mfma_f32_16x16x32_bf16 v[32:35], v[162:165], v[232:235], v[32:35]
	v_mfma_f32_16x16x32_bf16 v[16:19], v[162:165], v[240:243], v[16:19]
	s_setprio 0
	s_setprio 1
	v_mfma_f32_16x16x32_bf16 v[52:55], v[166:169], v[198:201], v[52:55]
	v_mfma_f32_16x16x32_bf16 v[36:39], v[166:169], v[220:223], v[36:39]
	v_mfma_f32_16x16x32_bf16 v[20:23], v[166:169], v[228:231], v[20:23]
	v_mfma_f32_16x16x32_bf16 v[8:11], v[166:169], v[236:239], v[8:11]
	v_mfma_f32_16x16x32_bf16 v[44:47], v[174:177], v[198:201], v[44:47]
	v_mfma_f32_16x16x32_bf16 v[28:31], v[174:177], v[220:223], v[28:31]
	v_mfma_f32_16x16x32_bf16 v[12:15], v[174:177], v[228:231], v[12:15]
	v_mfma_f32_16x16x32_bf16 v[4:7], v[174:177], v[236:239], v[4:7]
	v_mfma_f32_16x16x32_bf16 v[52:55], v[170:173], v[202:205], v[52:55]
	v_mfma_f32_16x16x32_bf16 v[36:39], v[170:173], v[224:227], v[36:39]
	v_mfma_f32_16x16x32_bf16 v[20:23], v[170:173], v[232:235], v[20:23]
	v_mfma_f32_16x16x32_bf16 v[8:11], v[170:173], v[240:243], v[8:11]
	v_mfma_f32_16x16x32_bf16 v[44:47], v[178:181], v[202:205], v[44:47]
	v_mfma_f32_16x16x32_bf16 v[28:31], v[178:181], v[224:227], v[28:31]
	v_mfma_f32_16x16x32_bf16 v[12:15], v[178:181], v[232:235], v[12:15]
	v_mfma_f32_16x16x32_bf16 v[4:7], v[178:181], v[240:243], v[4:7]
	s_setprio 0
	s_barrier
	s_add_i32 s48, s48, 2
	s_add_u32 s18, s18, 0x100
	s_addc_u32 s19, s19, 0
	s_add_u32 s46, s46, 0x100
	s_addc_u32 s47, s47, 0
	s_cmp_gt_u32 s48, 29
	s_cbranch_scc0 .LBB11_638
	s_and_b64 vcc, exec, s[4:5]
	s_cbranch_vccz .LBB11_641
	s_barrier

; #define PG8_STAGE(bufoff, gbase, voff) do { _Pragma("unroll") for (int _i = 0; _i < 2; ++_i) \
;         __builtin_amdgcn_global_load_lds((const unsigned*)((const char*)(gbase) + (voff)[_i]), (PG8_LAS unsigned*)(lds + (bufoff) + ldsw + _i * 8192), 16, 0, 0); } while (0)
; #define PG8_LDA(dst, b, h) do { _Pragma("unroll") for (int m = 0; m < 4; ++m) _Pragma("unroll") for (int k = 0; k < 2; ++k) dst[m][k] = *(const PG8_LAS bf16x8*)(lds + PG8_SA(b, h) + aoff + m * 2048 + k * 1024); } while (0)
; #define PG8_LDB(dst, b, h) do { _Pragma("unroll") for (int n = 0; n < 2; ++n) _Pragma("unroll") for (int k = 0; k < 2; ++k) dst[n][k] = *(const PG8_LAS bf16x8*)(lds + PG8_SB(b, h) + boff + n * 2048 + k * 1024); } while (0)
; #define PG8_MMA(ai, bj, At, Bt) do { __builtin_amdgcn_s_setprio(1); _Pragma("unroll") for (int m = 0; m < 4; ++m) _Pragma("unroll") for (int n = 0; n < 2; ++n) _Pragma("unroll") for (int k = 0; k < 2; ++k) \
;         acc[ai][bj][m][n] = __builtin_amdgcn_mfma_f32_16x16x32_bf16(Bt[n][k], At[m][k], acc[ai][bj][m][n], 0, 0, 0); __builtin_amdgcn_s_setprio(0); } while (0)
; #define PG8_WAIT_V(n) asm volatile("s_waitcnt vmcnt(" #n ")" ::: "memory")
; #define PG8_WAIT_L(n) asm volatile("s_waitcnt lgkmcnt(" #n ")" ::: "memory")
; #define PG8_BAR __builtin_amdgcn_s_barrier()
; #define PG8_SCHED __builtin_amdgcn_sched_barrier(0)
; template <class Epi, class Sched, bool ALIGN_EPI = false, bool SP2 = false>
; __device__ __forceinline__ void gemm_phase(PG8_LAS unsigned char* lds, const Gemm g, const Sched& S, const Epi& E) {
;     ...
;             PG8_LDB(B0, 0, 0); PG8_LDB(B1, 0, 1); PG8_SCHED; PG8_LDA(At, 0, 0); PG8_STAGE(PG8_SA(1, 1), a1 + hstep, voffA);
;             PG8_WAIT_V(8); PG8_WAIT_L(0); PG8_BAR; PG8_MMA(0, 0, At, B0); PG8_MMA(0, 1, At, B1); PG8_BAR; PG8_SCHED;
;             PG8_LDA(At, 0, 1); PG8_STAGE(PG8_SB(0, 0), b2, voffB); PG8_STAGE(PG8_SB(0, 1), b2 + hstep, voffB); PG8_STAGE(PG8_SA(0, 0), a2, voffA);
.LBB11_913:
	s_add_u32 s16, s14, 0xfff80080
	s_addc_u32 s17, s15, -1
	s_add_i32 s44, 0, 0x10000
	s_cmp_eq_u32 s43, 28
	s_cselect_b32 s19, s9, s17
	s_cselect_b32 s18, s37, s16
	v_add_u32_e32 v144, s44, v146
	s_cselect_b32 s17, s7, s42
	s_cselect_b32 s16, s40, s41
	s_add_i32 s46, 0, 0x14000
	ds_read_b128 v[150:153], v144
	ds_read_b128 v[154:157], v144 offset:1024
	ds_read_b128 v[158:161], v144 offset:2048
	ds_read_b128 v[162:165], v144 offset:3072
	v_add_u32_e32 v144, s46, v146
	ds_read_b128 v[166:169], v144
	ds_read_b128 v[170:173], v144 offset:1024
	ds_read_b128 v[174:177], v144 offset:2048
	ds_read_b128 v[178:181], v144 offset:3072
	v_lshl_add_u64 v[144:145], s[14:15], 0, v[140:141]
	s_add_i32 m0, s24, 0xc000
	ds_read_b128 v[198:201], v148
	ds_read_b128 v[202:205], v148 offset:1024
	ds_read_b128 v[220:223], v148 offset:2048
	ds_read_b128 v[224:227], v148 offset:3072
	ds_read_b128 v[228:231], v148 offset:4096
	ds_read_b128 v[232:235], v148 offset:5120
	ds_read_b128 v[236:239], v148 offset:6144
	ds_read_b128 v[240:243], v148 offset:7168
	global_load_lds_dwordx4 v[144:145], off
	v_lshl_add_u64 v[144:145], s[14:15], 0, v[142:143]
	s_add_i32 m0, s24, 0xe000
	s_nop 0
	global_load_lds_dwordx4 v[144:145], off
	s_waitcnt vmcnt(8)
	s_waitcnt lgkmcnt(0)
	s_barrier
	s_setprio 1
	s_waitcnt lgkmcnt(0)
	v_mfma_f32_16x16x32_bf16 v[128:131], v[150:153], v[198:201], v[128:131]
	v_mfma_f32_16x16x32_bf16 v[120:123], v[150:153], v[220:223], v[120:123]
	v_mfma_f32_16x16x32_bf16 v[104:107], v[150:153], v[228:231], v[104:107]
	v_mfma_f32_16x16x32_bf16 v[88:91], v[150:153], v[236:239], v[88:91]
	v_mfma_f32_16x16x32_bf16 v[124:127], v[158:161], v[198:201], v[124:127]
	v_mfma_f32_16x16x32_bf16 v[112:115], v[158:161], v[220:223], v[112:115]
	v_mfma_f32_16x16x32_bf16 v[96:99], v[158:161], v[228:231], v[96:99]
	v_mfma_f32_16x16x32_bf16 v[80:83], v[158:161], v[236:239], v[80:83]
	v_mfma_f32_16x16x32_bf16 v[128:131], v[154:157], v[202:205], v[128:131]
	v_mfma_f32_16x16x32_bf16 v[120:123], v[154:157], v[224:227], v[120:123]
	v_mfma_f32_16x16x32_bf16 v[104:107], v[154:157], v[232:235], v[104:107]
	v_mfma_f32_16x16x32_bf16 v[88:91], v[154:157], v[240:243], v[88:91]
	v_mfma_f32_16x16x32_bf16 v[124:127], v[162:165], v[202:205], v[124:127]
	v_mfma_f32_16x16x32_bf16 v[112:115], v[162:165], v[224:227], v[112:115]
	v_mfma_f32_16x16x32_bf16 v[96:99], v[162:165], v[232:235], v[96:99]
	v_mfma_f32_16x16x32_bf16 v[80:83], v[162:165], v[240:243], v[80:83]
	s_setprio 0
	s_setprio 1
	v_mfma_f32_16x16x32_bf16 v[116:119], v[166:169], v[198:201], v[116:119]
	v_mfma_f32_16x16x32_bf16 v[100:103], v[166:169], v[220:223], v[100:103]
	v_mfma_f32_16x16x32_bf16 v[84:87], v[166:169], v[228:231], v[84:87]
	v_mfma_f32_16x16x32_bf16 v[72:75], v[166:169], v[236:239], v[72:75]
	v_mfma_f32_16x16x32_bf16 v[108:111], v[174:177], v[198:201], v[108:111]
	v_mfma_f32_16x16x32_bf16 v[92:95], v[174:177], v[220:223], v[92:95]
	v_mfma_f32_16x16x32_bf16 v[76:79], v[174:177], v[228:231], v[76:79]
	v_mfma_f32_16x16x32_bf16 v[68:71], v[174:177], v[236:239], v[68:71]
	v_mfma_f32_16x16x32_bf16 v[116:119], v[170:173], v[202:205], v[116:119]
	v_mfma_f32_16x16x32_bf16 v[100:103], v[170:173], v[224:227], v[100:103]
	v_mfma_f32_16x16x32_bf16 v[84:87], v[170:173], v[232:235], v[84:87]
	v_mfma_f32_16x16x32_bf16 v[72:75], v[170:173], v[240:243], v[72:75]
	v_mfma_f32_16x16x32_bf16 v[108:111], v[178:181], v[202:205], v[108:111]
	v_mfma_f32_16x16x32_bf16 v[92:95], v[178:181], v[224:227], v[92:95]
	v_mfma_f32_16x16x32_bf16 v[76:79], v[178:181], v[232:235], v[76:79]
	v_mfma_f32_16x16x32_bf16 v[68:71], v[178:181], v[240:243], v[68:71]
	s_setprio 0
	s_barrier
	s_add_i32 s44, s44, s23
	v_lshl_add_u64 v[144:145], s[16:17], 0, v[2:3]
	s_mov_b32 m0, s44
	ds_read_b128 v[198:201], v148 offset:16384
	ds_read_b128 v[202:205], v148 offset:17408
	ds_read_b128 v[220:223], v148 offset:18432
	ds_read_b128 v[224:227], v148 offset:19456
	ds_read_b128 v[228:231], v148 offset:20480
	ds_read_b128 v[232:235], v148 offset:21504
	ds_read_b128 v[236:239], v148 offset:22528
	ds_read_b128 v[240:243], v148 offset:23552
	global_load_lds_dwordx4 v[144:145], off
	s_add_i32 m0, s44, 0x2000
	s_add_u32 s44, s16, 0x80000
	v_lshl_add_u64 v[184:185], s[16:17], 0, v[132:133]
	s_addc_u32 s45, s17, 0
	s_add_i32 s46, s46, s23
	global_load_lds_dwordx4 v[184:185], off
	v_lshl_add_u64 v[186:187], s[44:45], 0, v[2:3]
	s_mov_b32 m0, s46
	v_lshl_add_u64 v[196:197], s[18:19], 0, v[134:135]
	global_load_lds_dwordx4 v[186:187], off
	v_lshl_add_u64 v[186:187], s[44:45], 0, v[132:133]
	s_add_i32 m0, s46, 0x2000
	s_nop 0
	global_load_lds_dwordx4 v[186:187], off
	v_lshl_add_u64 v[186:187], s[18:19], 0, v[136:137]
	s_mov_b32 m0, s24
	s_nop 0
	global_load_lds_dwordx4 v[186:187], off
	s_mov_b32 m0, s25
	s_nop 0
	global_load_lds_dwordx4 v[196:197], off
	s_waitcnt vmcnt(8)
	s_waitcnt lgkmcnt(0)
	s_barrier
; #define PG8_STAGE(bufoff, gbase, voff) do { _Pragma("unroll") for (int _i = 0; _i < 2; ++_i) \
;         __builtin_amdgcn_global_load_lds((const unsigned*)((const char*)(gbase) + (voff)[_i]), (PG8_LAS unsigned*)(lds + (bufoff) + ldsw + _i * 8192), 16, 0, 0); } while (0)
; #define PG8_LDA(dst, b, h) do { _Pragma("unroll") for (int m = 0; m < 4; ++m) _Pragma("unroll") for (int k = 0; k < 2; ++k) dst[m][k] = *(const PG8_LAS bf16x8*)(lds + PG8_SA(b, h) + aoff + m * 2048 + k * 1024); } while (0)
; #define PG8_LDB(dst, b, h) do { _Pragma("unroll") for (int n = 0; n < 2; ++n) _Pragma("unroll") for (int k = 0; k < 2; ++k) dst[n][k] = *(const PG8_LAS bf16x8*)(lds + PG8_SB(b, h) + boff + n * 2048 + k * 1024); } while (0)
; #define PG8_MMA(ai, bj, At, Bt) do { __builtin_amdgcn_s_setprio(1); _Pragma("unroll") for (int m = 0; m < 4; ++m) _Pragma("unroll") for (int n = 0; n < 2; ++n) _Pragma("unroll") for (int k = 0; k < 2; ++k) \
;         acc[ai][bj][m][n] = __builtin_amdgcn_mfma_f32_16x16x32_bf16(Bt[n][k], At[m][k], acc[ai][bj][m][n], 0, 0, 0); __builtin_amdgcn_s_setprio(0); } while (0)
; #define PG8_WAIT_V(n) asm volatile("s_waitcnt vmcnt(" #n ")" ::: "memory")
; #define PG8_WAIT_L(n) asm volatile("s_waitcnt lgkmcnt(" #n ")" ::: "memory")
; #define PG8_BAR __builtin_amdgcn_s_barrier()
; #define PG8_SCHED __builtin_amdgcn_sched_barrier(0)
; template <class Epi, class Sched, bool ALIGN_EPI = false, bool SP2 = false>
; __device__ __forceinline__ void gemm_phase(PG8_LAS unsigned char* lds, const Gemm g, const Sched& S, const Epi& E) {
;     ...
;             PG8_WAIT_V(8); PG8_WAIT_L(0); PG8_BAR; PG8_MMA(1, 0, At, B0); PG8_MMA(1, 1, At, B1); PG8_BAR; PG8_SCHED;
;             PG8_LDB(B0, 1, 0); PG8_LDB(B1, 1, 1); PG8_SCHED; PG8_LDA(At, 1, 0); PG8_STAGE(PG8_SA(0, 1), a2 + hstep, voffA);
;             PG8_WAIT_V(8); PG8_WAIT_L(0); PG8_BAR; PG8_MMA(0, 0, At, B0); PG8_MMA(0, 1, At, B1); PG8_BAR; PG8_SCHED;
	s_setprio 1
	s_waitcnt lgkmcnt(0)
	v_mfma_f32_16x16x32_bf16 v[64:67], v[150:153], v[198:201], v[64:67]
	v_mfma_f32_16x16x32_bf16 v[56:59], v[150:153], v[220:223], v[56:59]
	v_mfma_f32_16x16x32_bf16 v[40:43], v[150:153], v[228:231], v[40:43]
	v_mfma_f32_16x16x32_bf16 v[24:27], v[150:153], v[236:239], v[24:27]
	v_mfma_f32_16x16x32_bf16 v[60:63], v[158:161], v[198:201], v[60:63]
	v_mfma_f32_16x16x32_bf16 v[48:51], v[158:161], v[220:223], v[48:51]
	v_mfma_f32_16x16x32_bf16 v[32:35], v[158:161], v[228:231], v[32:35]
	v_mfma_f32_16x16x32_bf16 v[16:19], v[158:161], v[236:239], v[16:19]
	v_mfma_f32_16x16x32_bf16 v[64:67], v[154:157], v[202:205], v[64:67]
	v_mfma_f32_16x16x32_bf16 v[56:59], v[154:157], v[224:227], v[56:59]
	v_mfma_f32_16x16x32_bf16 v[40:43], v[154:157], v[232:235], v[40:43]
	v_mfma_f32_16x16x32_bf16 v[24:27], v[154:157], v[240:243], v[24:27]
	v_mfma_f32_16x16x32_bf16 v[60:63], v[162:165], v[202:205], v[60:63]
	v_mfma_f32_16x16x32_bf16 v[48:51], v[162:165], v[224:227], v[48:51]
	v_mfma_f32_16x16x32_bf16 v[32:35], v[162:165], v[232:235], v[32:35]
	v_mfma_f32_16x16x32_bf16 v[16:19], v[162:165], v[240:243], v[16:19]
	s_setprio 0
	s_setprio 1
	v_mfma_f32_16x16x32_bf16 v[52:55], v[166:169], v[198:201], v[52:55]
	v_mfma_f32_16x16x32_bf16 v[36:39], v[166:169], v[220:223], v[36:39]
	v_mfma_f32_16x16x32_bf16 v[20:23], v[166:169], v[228:231], v[20:23]
	v_mfma_f32_16x16x32_bf16 v[8:11], v[166:169], v[236:239], v[8:11]
	v_mfma_f32_16x16x32_bf16 v[44:47], v[174:177], v[198:201], v[44:47]
	v_mfma_f32_16x16x32_bf16 v[28:31], v[174:177], v[220:223], v[28:31]
	v_mfma_f32_16x16x32_bf16 v[12:15], v[174:177], v[228:231], v[12:15]
	v_mfma_f32_16x16x32_bf16 v[4:7], v[174:177], v[236:239], v[4:7]
	v_mfma_f32_16x16x32_bf16 v[52:55], v[170:173], v[202:205], v[52:55]
	v_mfma_f32_16x16x32_bf16 v[36:39], v[170:173], v[224:227], v[36:39]
	v_mfma_f32_16x16x32_bf16 v[20:23], v[170:173], v[232:235], v[20:23]
	v_mfma_f32_16x16x32_bf16 v[8:11], v[170:173], v[240:243], v[8:11]
	v_mfma_f32_16x16x32_bf16 v[44:47], v[178:181], v[202:205], v[44:47]
	v_mfma_f32_16x16x32_bf16 v[28:31], v[178:181], v[224:227], v[28:31]
	v_mfma_f32_16x16x32_bf16 v[12:15], v[178:181], v[232:235], v[12:15]
	v_mfma_f32_16x16x32_bf16 v[4:7], v[178:181], v[240:243], v[4:7]
	s_setprio 0
	s_barrier
	s_add_i32 s44, 0, 0x18000
	v_add_u32_e32 v149, s44, v146
	s_add_i32 s45, 0, 0x1c000
	ds_read_b128 v[150:153], v149
	ds_read_b128 v[154:157], v149 offset:1024
	ds_read_b128 v[158:161], v149 offset:2048
	ds_read_b128 v[162:165], v149 offset:3072
	v_add_u32_e32 v149, s45, v146
	ds_read_b128 v[166:169], v149
	ds_read_b128 v[170:173], v149 offset:1024
	ds_read_b128 v[174:177], v149 offset:2048
	ds_read_b128 v[178:181], v149 offset:3072
	s_add_u32 s18, s18, 0x80000
	s_addc_u32 s19, s19, 0
	s_mov_b32 m0, s26
	v_lshl_add_u64 v[206:207], s[18:19], 0, v[136:137]
	ds_read_b128 v[198:201], v148 offset:32768
	ds_read_b128 v[202:205], v148 offset:33792
	ds_read_b128 v[220:223], v148 offset:34816
	ds_read_b128 v[224:227], v148 offset:35840
	ds_read_b128 v[228:231], v148 offset:36864
	ds_read_b128 v[232:235], v148 offset:37888
	ds_read_b128 v[236:239], v148 offset:38912
	ds_read_b128 v[240:243], v148 offset:39936
	global_load_lds_dwordx4 v[206:207], off
	v_lshl_add_u64 v[206:207], s[18:19], 0, v[134:135]
	s_mov_b32 m0, s27
	s_nop 0
	global_load_lds_dwordx4 v[206:207], off
	s_waitcnt vmcnt(8)
	s_waitcnt lgkmcnt(0)
	s_barrier
	s_setprio 1
	s_waitcnt lgkmcnt(0)
	v_mfma_f32_16x16x32_bf16 v[128:131], v[150:153], v[198:201], v[128:131]
	v_mfma_f32_16x16x32_bf16 v[120:123], v[150:153], v[220:223], v[120:123]
	v_mfma_f32_16x16x32_bf16 v[104:107], v[150:153], v[228:231], v[104:107]
	v_mfma_f32_16x16x32_bf16 v[88:91], v[150:153], v[236:239], v[88:91]
	v_mfma_f32_16x16x32_bf16 v[124:127], v[158:161], v[198:201], v[124:127]
	v_mfma_f32_16x16x32_bf16 v[112:115], v[158:161], v[220:223], v[112:115]
	v_mfma_f32_16x16x32_bf16 v[96:99], v[158:161], v[228:231], v[96:99]
	v_mfma_f32_16x16x32_bf16 v[80:83], v[158:161], v[236:239], v[80:83]
	v_mfma_f32_16x16x32_bf16 v[128:131], v[154:157], v[202:205], v[128:131]
	v_mfma_f32_16x16x32_bf16 v[120:123], v[154:157], v[224:227], v[120:123]
	v_mfma_f32_16x16x32_bf16 v[104:107], v[154:157], v[232:235], v[104:107]
	v_mfma_f32_16x16x32_bf16 v[88:91], v[154:157], v[240:243], v[88:91]
	v_mfma_f32_16x16x32_bf16 v[124:127], v[162:165], v[202:205], v[124:127]
	v_mfma_f32_16x16x32_bf16 v[112:115], v[162:165], v[224:227], v[112:115]
	v_mfma_f32_16x16x32_bf16 v[96:99], v[162:165], v[232:235], v[96:99]
	v_mfma_f32_16x16x32_bf16 v[80:83], v[162:165], v[240:243], v[80:83]
	s_setprio 0
	s_setprio 1
	v_mfma_f32_16x16x32_bf16 v[116:119], v[166:169], v[198:201], v[116:119]
	v_mfma_f32_16x16x32_bf16 v[100:103], v[166:169], v[220:223], v[100:103]
	v_mfma_f32_16x16x32_bf16 v[84:87], v[166:169], v[228:231], v[84:87]
	v_mfma_f32_16x16x32_bf16 v[72:75], v[166:169], v[236:239], v[72:75]
	v_mfma_f32_16x16x32_bf16 v[108:111], v[174:177], v[198:201], v[108:111]
	v_mfma_f32_16x16x32_bf16 v[92:95], v[174:177], v[220:223], v[92:95]
	v_mfma_f32_16x16x32_bf16 v[76:79], v[174:177], v[228:231], v[76:79]
	v_mfma_f32_16x16x32_bf16 v[68:71], v[174:177], v[236:239], v[68:71]
	v_mfma_f32_16x16x32_bf16 v[116:119], v[170:173], v[202:205], v[116:119]
	v_mfma_f32_16x16x32_bf16 v[100:103], v[170:173], v[224:227], v[100:103]
	v_mfma_f32_16x16x32_bf16 v[84:87], v[170:173], v[232:235], v[84:87]
	v_mfma_f32_16x16x32_bf16 v[72:75], v[170:173], v[240:243], v[72:75]
	v_mfma_f32_16x16x32_bf16 v[108:111], v[178:181], v[202:205], v[108:111]
	v_mfma_f32_16x16x32_bf16 v[92:95], v[178:181], v[224:227], v[92:95]
	v_mfma_f32_16x16x32_bf16 v[76:79], v[178:181], v[232:235], v[76:79]
	v_mfma_f32_16x16x32_bf16 v[68:71], v[178:181], v[240:243], v[68:71]
	s_setprio 0
	s_barrier
; #define PG8_STAGE(bufoff, gbase, voff) do { _Pragma("unroll") for (int _i = 0; _i < 2; ++_i) \
;         __builtin_amdgcn_global_load_lds((const unsigned*)((const char*)(gbase) + (voff)[_i]), (PG8_LAS unsigned*)(lds + (bufoff) + ldsw + _i * 8192), 16, 0, 0); } while (0)
; #define PG8_LDA(dst, b, h) do { _Pragma("unroll") for (int m = 0; m < 4; ++m) _Pragma("unroll") for (int k = 0; k < 2; ++k) dst[m][k] = *(const PG8_LAS bf16x8*)(lds + PG8_SA(b, h) + aoff + m * 2048 + k * 1024); } while (0)
; #define PG8_MMA(ai, bj, At, Bt) do { __builtin_amdgcn_s_setprio(1); _Pragma("unroll") for (int m = 0; m < 4; ++m) _Pragma("unroll") for (int n = 0; n < 2; ++n) _Pragma("unroll") for (int k = 0; k < 2; ++k) \
;         acc[ai][bj][m][n] = __builtin_amdgcn_mfma_f32_16x16x32_bf16(Bt[n][k], At[m][k], acc[ai][bj][m][n], 0, 0, 0); __builtin_amdgcn_s_setprio(0); } while (0)
; #define PG8_WAIT_V(n) asm volatile("s_waitcnt vmcnt(" #n ")" ::: "memory")
; #define PG8_WAIT_L(n) asm volatile("s_waitcnt lgkmcnt(" #n ")" ::: "memory")
; #define PG8_BAR __builtin_amdgcn_s_barrier()
; #define PG8_SCHED __builtin_amdgcn_sched_barrier(0)
; template <class Epi, class Sched, bool ALIGN_EPI = false, bool SP2 = false>
; __device__ __forceinline__ void gemm_phase(PG8_LAS unsigned char* lds, const Gemm g, const Sched& S, const Epi& E) {
;     ...
;             PG8_LDA(At, 1, 1); PG8_STAGE(PG8_SB(1, 0), b3, voffB); PG8_STAGE(PG8_SB(1, 1), b3 + hstep, voffB); PG8_STAGE(PG8_SA(1, 0), a3, voffA);
;             PG8_WAIT_V(8); PG8_WAIT_L(0); PG8_BAR; PG8_MMA(1, 0, At, B0); PG8_MMA(1, 1, At, B1); PG8_BAR; PG8_SCHED;
	s_add_i32 s18, s44, s23
	v_lshl_add_u64 v[144:145], v[144:145], 0, s[34:35]
	s_mov_b32 m0, s18
	ds_read_b128 v[198:201], v148 offset:49152
	ds_read_b128 v[202:205], v148 offset:50176
	ds_read_b128 v[220:223], v148 offset:51200
	ds_read_b128 v[224:227], v148 offset:52224
	ds_read_b128 v[228:231], v148 offset:53248
	ds_read_b128 v[232:235], v148 offset:54272
	ds_read_b128 v[236:239], v148 offset:55296
	ds_read_b128 v[240:243], v148 offset:56320
	global_load_lds_dwordx4 v[144:145], off
	s_add_i32 m0, s18, 0x2000
	s_add_u32 s16, s16, 0x80080
	v_lshl_add_u64 v[144:145], v[184:185], 0, s[34:35]
	s_addc_u32 s17, s17, 0
	s_add_i32 s18, s45, s23
	global_load_lds_dwordx4 v[144:145], off
	v_lshl_add_u64 v[144:145], s[16:17], 0, v[2:3]
	s_mov_b32 m0, s18
	s_nop 0
	global_load_lds_dwordx4 v[144:145], off
	v_lshl_add_u64 v[144:145], s[16:17], 0, v[132:133]
	s_add_i32 m0, s18, 0x2000
	s_nop 0
	global_load_lds_dwordx4 v[144:145], off
	v_lshl_add_u64 v[144:145], v[186:187], 0, s[34:35]
	s_mov_b32 m0, s28
	s_nop 0
	global_load_lds_dwordx4 v[144:145], off
	v_lshl_add_u64 v[144:145], v[196:197], 0, s[34:35]
	s_mov_b32 m0, s29
	s_nop 0
	global_load_lds_dwordx4 v[144:145], off
	s_waitcnt vmcnt(8)
	s_waitcnt lgkmcnt(0)
	s_barrier
	s_setprio 1
	s_waitcnt lgkmcnt(0)
	v_mfma_f32_16x16x32_bf16 v[64:67], v[150:153], v[198:201], v[64:67]
	v_mfma_f32_16x16x32_bf16 v[56:59], v[150:153], v[220:223], v[56:59]
	v_mfma_f32_16x16x32_bf16 v[40:43], v[150:153], v[228:231], v[40:43]
	v_mfma_f32_16x16x32_bf16 v[24:27], v[150:153], v[236:239], v[24:27]
	v_mfma_f32_16x16x32_bf16 v[60:63], v[158:161], v[198:201], v[60:63]
	v_mfma_f32_16x16x32_bf16 v[48:51], v[158:161], v[220:223], v[48:51]
	v_mfma_f32_16x16x32_bf16 v[32:35], v[158:161], v[228:231], v[32:35]
	v_mfma_f32_16x16x32_bf16 v[16:19], v[158:161], v[236:239], v[16:19]
	v_mfma_f32_16x16x32_bf16 v[64:67], v[154:157], v[202:205], v[64:67]
	v_mfma_f32_16x16x32_bf16 v[56:59], v[154:157], v[224:227], v[56:59]
	v_mfma_f32_16x16x32_bf16 v[40:43], v[154:157], v[232:235], v[40:43]
	v_mfma_f32_16x16x32_bf16 v[24:27], v[154:157], v[240:243], v[24:27]
	v_mfma_f32_16x16x32_bf16 v[60:63], v[162:165], v[202:205], v[60:63]
	v_mfma_f32_16x16x32_bf16 v[48:51], v[162:165], v[224:227], v[48:51]
	v_mfma_f32_16x16x32_bf16 v[32:35], v[162:165], v[232:235], v[32:35]
	v_mfma_f32_16x16x32_bf16 v[16:19], v[162:165], v[240:243], v[16:19]
	s_setprio 0
	s_setprio 1
	v_mfma_f32_16x16x32_bf16 v[52:55], v[166:169], v[198:201], v[52:55]
	v_mfma_f32_16x16x32_bf16 v[36:39], v[166:169], v[220:223], v[36:39]
	v_mfma_f32_16x16x32_bf16 v[20:23], v[166:169], v[228:231], v[20:23]
	v_mfma_f32_16x16x32_bf16 v[8:11], v[166:169], v[236:239], v[8:11]
	v_mfma_f32_16x16x32_bf16 v[44:47], v[174:177], v[198:201], v[44:47]
	v_mfma_f32_16x16x32_bf16 v[28:31], v[174:177], v[220:223], v[28:31]
	v_mfma_f32_16x16x32_bf16 v[12:15], v[174:177], v[228:231], v[12:15]
	v_mfma_f32_16x16x32_bf16 v[4:7], v[174:177], v[236:239], v[4:7]
	v_mfma_f32_16x16x32_bf16 v[52:55], v[170:173], v[202:205], v[52:55]
	v_mfma_f32_16x16x32_bf16 v[36:39], v[170:173], v[224:227], v[36:39]
	v_mfma_f32_16x16x32_bf16 v[20:23], v[170:173], v[232:235], v[20:23]
	v_mfma_f32_16x16x32_bf16 v[8:11], v[170:173], v[240:243], v[8:11]
	v_mfma_f32_16x16x32_bf16 v[44:47], v[178:181], v[202:205], v[44:47]
	v_mfma_f32_16x16x32_bf16 v[28:31], v[178:181], v[224:227], v[28:31]
	v_mfma_f32_16x16x32_bf16 v[12:15], v[178:181], v[232:235], v[12:15]
	v_mfma_f32_16x16x32_bf16 v[4:7], v[178:181], v[240:243], v[4:7]
	s_setprio 0
	s_barrier
	s_add_i32 s43, s43, 2
	s_add_u32 s14, s14, 0x100
	s_addc_u32 s15, s15, 0
	s_add_u32 s41, s41, 0x100
	s_addc_u32 s42, s42, 0
	s_cmp_gt_u32 s43, 29
	s_cbranch_scc0 .LBB11_913
	s_and_b64 vcc, exec, s[4:5]
	s_cbranch_vccz .LBB11_916
	s_barrier

; #define PG8_STAGE(bufoff, gbase, voff) do { _Pragma("unroll") for (int _i = 0; _i < 2; ++_i) \
;         __builtin_amdgcn_global_load_lds((const unsigned*)((const char*)(gbase) + (voff)[_i]), (PG8_LAS unsigned*)(lds + (bufoff) + ldsw + _i * 8192), 16, 0, 0); } while (0)
; #define PG8_LDA(dst, b, h) do { _Pragma("unroll") for (int m = 0; m < 4; ++m) _Pragma("unroll") for (int k = 0; k < 2; ++k) dst[m][k] = *(const PG8_LAS bf16x8*)(lds + PG8_SA(b, h) + aoff + m * 2048 + k * 1024); } while (0)
; #define PG8_LDB(dst, b, h) do { _Pragma("unroll") for (int n = 0; n < 2; ++n) _Pragma("unroll") for (int k = 0; k < 2; ++k) dst[n][k] = *(const PG8_LAS bf16x8*)(lds + PG8_SB(b, h) + boff + n * 2048 + k * 1024); } while (0)
; #define PG8_MMA(ai, bj, At, Bt) do { __builtin_amdgcn_s_setprio(1); _Pragma("unroll") for (int m = 0; m < 4; ++m) _Pragma("unroll") for (int n = 0; n < 2; ++n) _Pragma("unroll") for (int k = 0; k < 2; ++k) \
;         acc[ai][bj][m][n] = __builtin_amdgcn_mfma_f32_16x16x32_bf16(Bt[n][k], At[m][k], acc[ai][bj][m][n], 0, 0, 0); __builtin_amdgcn_s_setprio(0); } while (0)
; #define PG8_WAIT_V(n) asm volatile("s_waitcnt vmcnt(" #n ")" ::: "memory")
; #define PG8_WAIT_L(n) asm volatile("s_waitcnt lgkmcnt(" #n ")" ::: "memory")
; #define PG8_BAR __builtin_amdgcn_s_barrier()
; #define PG8_SCHED __builtin_amdgcn_sched_barrier(0)
; template <class Epi, class Sched, bool ALIGN_EPI = false, bool SP2 = false>
; __device__ __forceinline__ void gemm_phase(PG8_LAS unsigned char* lds, const Gemm g, const Sched& S, const Epi& E) {
;     ...
;             PG8_LDB(B0, 0, 0); PG8_LDB(B1, 0, 1); PG8_SCHED; PG8_LDA(At, 0, 0); PG8_STAGE(PG8_SA(1, 1), a1 + hstep, voffA);
;             PG8_WAIT_V(8); PG8_WAIT_L(0); PG8_BAR; PG8_MMA(0, 0, At, B0); PG8_MMA(0, 1, At, B1); PG8_BAR; PG8_SCHED;
;             PG8_LDA(At, 0, 1); PG8_STAGE(PG8_SB(0, 0), b2, voffB); PG8_STAGE(PG8_SB(0, 1), b2 + hstep, voffB); PG8_STAGE(PG8_SA(0, 0), a2, voffA);
.LBB11_1071:
	s_add_u32 s16, s14, 0xfff80080
	s_addc_u32 s17, s15, -1
	s_add_i32 s46, 0, 0x10000
	s_cmp_eq_u32 s45, 28
	s_cselect_b32 s19, s9, s17
	s_cselect_b32 s18, s41, s16
	v_add_u32_e32 v2, s46, v168
	s_cselect_b32 s17, s7, s44
	s_cselect_b32 s16, s42, s43
	s_add_i32 s48, 0, 0x14000
	ds_read_b128 v[132:135], v2
	ds_read_b128 v[136:139], v2 offset:1024
	ds_read_b128 v[140:143], v2 offset:2048
	ds_read_b128 v[144:147], v2 offset:3072
	v_add_u32_e32 v2, s48, v168
	ds_read_b128 v[170:173], v2
	ds_read_b128 v[174:177], v2 offset:1024
	ds_read_b128 v[178:181], v2 offset:2048
	ds_read_b128 v[198:201], v2 offset:3072
	v_lshl_add_u64 v[166:167], s[14:15], 0, v[162:163]
	s_add_i32 m0, s25, 0xc000
	ds_read_b128 v[202:205], v169
	ds_read_b128 v[220:223], v169 offset:1024
	ds_read_b128 v[224:227], v169 offset:2048
	ds_read_b128 v[228:231], v169 offset:3072
	ds_read_b128 v[232:235], v169 offset:4096
	ds_read_b128 v[236:239], v169 offset:5120
	ds_read_b128 v[240:243], v169 offset:6144
	ds_read_b128 v[244:247], v169 offset:7168
	global_load_lds_dwordx4 v[166:167], off
	v_lshl_add_u64 v[166:167], s[14:15], 0, v[164:165]
	s_add_i32 m0, s25, 0xe000
	s_nop 0
	global_load_lds_dwordx4 v[166:167], off
	s_waitcnt vmcnt(8)
	s_waitcnt lgkmcnt(0)
	s_barrier
	s_setprio 1
	s_waitcnt lgkmcnt(0)
	v_mfma_f32_16x16x32_bf16 v[128:131], v[132:135], v[202:205], v[128:131]
	v_mfma_f32_16x16x32_bf16 v[120:123], v[132:135], v[224:227], v[120:123]
	v_mfma_f32_16x16x32_bf16 v[104:107], v[132:135], v[232:235], v[104:107]
	v_mfma_f32_16x16x32_bf16 v[88:91], v[132:135], v[240:243], v[88:91]
	v_mfma_f32_16x16x32_bf16 v[124:127], v[140:143], v[202:205], v[124:127]
	v_mfma_f32_16x16x32_bf16 v[112:115], v[140:143], v[224:227], v[112:115]
	v_mfma_f32_16x16x32_bf16 v[96:99], v[140:143], v[232:235], v[96:99]
	v_mfma_f32_16x16x32_bf16 v[80:83], v[140:143], v[240:243], v[80:83]
	v_mfma_f32_16x16x32_bf16 v[128:131], v[136:139], v[220:223], v[128:131]
	v_mfma_f32_16x16x32_bf16 v[120:123], v[136:139], v[228:231], v[120:123]
	v_mfma_f32_16x16x32_bf16 v[104:107], v[136:139], v[236:239], v[104:107]
	v_mfma_f32_16x16x32_bf16 v[88:91], v[136:139], v[244:247], v[88:91]
	v_mfma_f32_16x16x32_bf16 v[124:127], v[144:147], v[220:223], v[124:127]
	v_mfma_f32_16x16x32_bf16 v[112:115], v[144:147], v[228:231], v[112:115]
	v_mfma_f32_16x16x32_bf16 v[96:99], v[144:147], v[236:239], v[96:99]
	v_mfma_f32_16x16x32_bf16 v[80:83], v[144:147], v[244:247], v[80:83]
	s_setprio 0
	s_setprio 1
	v_mfma_f32_16x16x32_bf16 v[116:119], v[170:173], v[202:205], v[116:119]
	v_mfma_f32_16x16x32_bf16 v[100:103], v[170:173], v[224:227], v[100:103]
	v_mfma_f32_16x16x32_bf16 v[84:87], v[170:173], v[232:235], v[84:87]
	v_mfma_f32_16x16x32_bf16 v[72:75], v[170:173], v[240:243], v[72:75]
	v_mfma_f32_16x16x32_bf16 v[108:111], v[178:181], v[202:205], v[108:111]
	v_mfma_f32_16x16x32_bf16 v[92:95], v[178:181], v[224:227], v[92:95]
	v_mfma_f32_16x16x32_bf16 v[76:79], v[178:181], v[232:235], v[76:79]
	v_mfma_f32_16x16x32_bf16 v[68:71], v[178:181], v[240:243], v[68:71]
	v_mfma_f32_16x16x32_bf16 v[116:119], v[174:177], v[220:223], v[116:119]
	v_mfma_f32_16x16x32_bf16 v[100:103], v[174:177], v[228:231], v[100:103]
	v_mfma_f32_16x16x32_bf16 v[84:87], v[174:177], v[236:239], v[84:87]
	v_mfma_f32_16x16x32_bf16 v[72:75], v[174:177], v[244:247], v[72:75]
	v_mfma_f32_16x16x32_bf16 v[108:111], v[198:201], v[220:223], v[108:111]
	v_mfma_f32_16x16x32_bf16 v[92:95], v[198:201], v[228:231], v[92:95]
	v_mfma_f32_16x16x32_bf16 v[76:79], v[198:201], v[236:239], v[76:79]
	v_mfma_f32_16x16x32_bf16 v[68:71], v[198:201], v[244:247], v[68:71]
	s_setprio 0
	s_barrier
	s_add_i32 s46, s46, s24
	v_lshl_add_u64 v[166:167], s[16:17], 0, v[154:155]
	s_mov_b32 m0, s46
	ds_read_b128 v[202:205], v169 offset:16384
	ds_read_b128 v[220:223], v169 offset:17408
	ds_read_b128 v[224:227], v169 offset:18432
	ds_read_b128 v[228:231], v169 offset:19456
	ds_read_b128 v[232:235], v169 offset:20480
	ds_read_b128 v[236:239], v169 offset:21504
	ds_read_b128 v[240:243], v169 offset:22528
	ds_read_b128 v[244:247], v169 offset:23552
	global_load_lds_dwordx4 v[166:167], off
	s_add_i32 m0, s46, 0x2000
	s_add_u32 s46, s16, 0x80000
	v_lshl_add_u64 v[196:197], s[16:17], 0, v[150:151]
	s_addc_u32 s47, s17, 0
	s_add_i32 s48, s48, s24
	global_load_lds_dwordx4 v[196:197], off
	v_lshl_add_u64 v[206:207], s[46:47], 0, v[154:155]
	s_mov_b32 m0, s48
	v_lshl_add_u64 v[184:185], s[18:19], 0, v[152:153]
	global_load_lds_dwordx4 v[206:207], off
	v_lshl_add_u64 v[206:207], s[46:47], 0, v[150:151]
	s_add_i32 m0, s48, 0x2000
	s_nop 0
	global_load_lds_dwordx4 v[206:207], off
	v_lshl_add_u64 v[206:207], s[18:19], 0, v[156:157]
	s_mov_b32 m0, s25
	s_nop 0
	global_load_lds_dwordx4 v[206:207], off
	s_mov_b32 m0, s26
	s_nop 0
	global_load_lds_dwordx4 v[184:185], off
	s_waitcnt vmcnt(8)
	s_waitcnt lgkmcnt(0)
	s_barrier
; #define PG8_STAGE(bufoff, gbase, voff) do { _Pragma("unroll") for (int _i = 0; _i < 2; ++_i) \
;         __builtin_amdgcn_global_load_lds((const unsigned*)((const char*)(gbase) + (voff)[_i]), (PG8_LAS unsigned*)(lds + (bufoff) + ldsw + _i * 8192), 16, 0, 0); } while (0)
; #define PG8_LDA(dst, b, h) do { _Pragma("unroll") for (int m = 0; m < 4; ++m) _Pragma("unroll") for (int k = 0; k < 2; ++k) dst[m][k] = *(const PG8_LAS bf16x8*)(lds + PG8_SA(b, h) + aoff + m * 2048 + k * 1024); } while (0)
; #define PG8_LDB(dst, b, h) do { _Pragma("unroll") for (int n = 0; n < 2; ++n) _Pragma("unroll") for (int k = 0; k < 2; ++k) dst[n][k] = *(const PG8_LAS bf16x8*)(lds + PG8_SB(b, h) + boff + n * 2048 + k * 1024); } while (0)
; #define PG8_MMA(ai, bj, At, Bt) do { __builtin_amdgcn_s_setprio(1); _Pragma("unroll") for (int m = 0; m < 4; ++m) _Pragma("unroll") for (int n = 0; n < 2; ++n) _Pragma("unroll") for (int k = 0; k < 2; ++k) \
;         acc[ai][bj][m][n] = __builtin_amdgcn_mfma_f32_16x16x32_bf16(Bt[n][k], At[m][k], acc[ai][bj][m][n], 0, 0, 0); __builtin_amdgcn_s_setprio(0); } while (0)
; #define PG8_WAIT_V(n) asm volatile("s_waitcnt vmcnt(" #n ")" ::: "memory")
; #define PG8_WAIT_L(n) asm volatile("s_waitcnt lgkmcnt(" #n ")" ::: "memory")
; #define PG8_BAR __builtin_amdgcn_s_barrier()
; #define PG8_SCHED __builtin_amdgcn_sched_barrier(0)
; template <class Epi, class Sched, bool ALIGN_EPI = false, bool SP2 = false>
; __device__ __forceinline__ void gemm_phase(PG8_LAS unsigned char* lds, const Gemm g, const Sched& S, const Epi& E) {
;     ...
;             PG8_WAIT_V(8); PG8_WAIT_L(0); PG8_BAR; PG8_MMA(1, 0, At, B0); PG8_MMA(1, 1, At, B1); PG8_BAR; PG8_SCHED;
;             PG8_LDB(B0, 1, 0); PG8_LDB(B1, 1, 1); PG8_SCHED; PG8_LDA(At, 1, 0); PG8_STAGE(PG8_SA(0, 1), a2 + hstep, voffA);
;             PG8_WAIT_V(8); PG8_WAIT_L(0); PG8_BAR; PG8_MMA(0, 0, At, B0); PG8_MMA(0, 1, At, B1); PG8_BAR; PG8_SCHED;
	s_setprio 1
	s_waitcnt lgkmcnt(0)
	v_mfma_f32_16x16x32_bf16 v[64:67], v[132:135], v[202:205], v[64:67]
	v_mfma_f32_16x16x32_bf16 v[56:59], v[132:135], v[224:227], v[56:59]
	v_mfma_f32_16x16x32_bf16 v[40:43], v[132:135], v[232:235], v[40:43]
	v_mfma_f32_16x16x32_bf16 v[24:27], v[132:135], v[240:243], v[24:27]
	v_mfma_f32_16x16x32_bf16 v[60:63], v[140:143], v[202:205], v[60:63]
	v_mfma_f32_16x16x32_bf16 v[48:51], v[140:143], v[224:227], v[48:51]
	v_mfma_f32_16x16x32_bf16 v[32:35], v[140:143], v[232:235], v[32:35]
	v_mfma_f32_16x16x32_bf16 v[16:19], v[140:143], v[240:243], v[16:19]
	v_mfma_f32_16x16x32_bf16 v[64:67], v[136:139], v[220:223], v[64:67]
	v_mfma_f32_16x16x32_bf16 v[56:59], v[136:139], v[228:231], v[56:59]
	v_mfma_f32_16x16x32_bf16 v[40:43], v[136:139], v[236:239], v[40:43]
	v_mfma_f32_16x16x32_bf16 v[24:27], v[136:139], v[244:247], v[24:27]
	v_mfma_f32_16x16x32_bf16 v[60:63], v[144:147], v[220:223], v[60:63]
	v_mfma_f32_16x16x32_bf16 v[48:51], v[144:147], v[228:231], v[48:51]
	v_mfma_f32_16x16x32_bf16 v[32:35], v[144:147], v[236:239], v[32:35]
	v_mfma_f32_16x16x32_bf16 v[16:19], v[144:147], v[244:247], v[16:19]
	s_setprio 0
	s_setprio 1
	v_mfma_f32_16x16x32_bf16 v[52:55], v[170:173], v[202:205], v[52:55]
	v_mfma_f32_16x16x32_bf16 v[36:39], v[170:173], v[224:227], v[36:39]
	v_mfma_f32_16x16x32_bf16 v[20:23], v[170:173], v[232:235], v[20:23]
	v_mfma_f32_16x16x32_bf16 v[8:11], v[170:173], v[240:243], v[8:11]
	v_mfma_f32_16x16x32_bf16 v[44:47], v[178:181], v[202:205], v[44:47]
	v_mfma_f32_16x16x32_bf16 v[28:31], v[178:181], v[224:227], v[28:31]
	v_mfma_f32_16x16x32_bf16 v[12:15], v[178:181], v[232:235], v[12:15]
	v_mfma_f32_16x16x32_bf16 v[4:7], v[178:181], v[240:243], v[4:7]
	v_mfma_f32_16x16x32_bf16 v[52:55], v[174:177], v[220:223], v[52:55]
	v_mfma_f32_16x16x32_bf16 v[36:39], v[174:177], v[228:231], v[36:39]
	v_mfma_f32_16x16x32_bf16 v[20:23], v[174:177], v[236:239], v[20:23]
	v_mfma_f32_16x16x32_bf16 v[8:11], v[174:177], v[244:247], v[8:11]
	v_mfma_f32_16x16x32_bf16 v[44:47], v[198:201], v[220:223], v[44:47]
	v_mfma_f32_16x16x32_bf16 v[28:31], v[198:201], v[228:231], v[28:31]
	v_mfma_f32_16x16x32_bf16 v[12:15], v[198:201], v[236:239], v[12:15]
	v_mfma_f32_16x16x32_bf16 v[4:7], v[198:201], v[244:247], v[4:7]
	s_setprio 0
	s_barrier
	s_add_i32 s46, 0, 0x18000
	v_add_u32_e32 v2, s46, v168
	s_add_i32 s47, 0, 0x1c000
	ds_read_b128 v[132:135], v2
	ds_read_b128 v[136:139], v2 offset:1024
	ds_read_b128 v[140:143], v2 offset:2048
	ds_read_b128 v[144:147], v2 offset:3072
	v_add_u32_e32 v2, s47, v168
	ds_read_b128 v[170:173], v2
	ds_read_b128 v[174:177], v2 offset:1024
	ds_read_b128 v[178:181], v2 offset:2048
	ds_read_b128 v[198:201], v2 offset:3072
	s_add_u32 s18, s18, 0x80000
	s_addc_u32 s19, s19, 0
	s_mov_b32 m0, s27
	v_lshl_add_u64 v[186:187], s[18:19], 0, v[156:157]
	ds_read_b128 v[202:205], v169 offset:32768
	ds_read_b128 v[220:223], v169 offset:33792
	ds_read_b128 v[224:227], v169 offset:34816
	ds_read_b128 v[228:231], v169 offset:35840
	ds_read_b128 v[232:235], v169 offset:36864
	ds_read_b128 v[236:239], v169 offset:37888
	ds_read_b128 v[240:243], v169 offset:38912
	ds_read_b128 v[244:247], v169 offset:39936
	global_load_lds_dwordx4 v[186:187], off
	v_lshl_add_u64 v[186:187], s[18:19], 0, v[152:153]
	s_mov_b32 m0, s28
	s_nop 0
	global_load_lds_dwordx4 v[186:187], off
	s_waitcnt vmcnt(8)
	s_waitcnt lgkmcnt(0)
	s_barrier
	s_setprio 1
	s_waitcnt lgkmcnt(0)
	v_mfma_f32_16x16x32_bf16 v[128:131], v[132:135], v[202:205], v[128:131]
	v_mfma_f32_16x16x32_bf16 v[120:123], v[132:135], v[224:227], v[120:123]
	v_mfma_f32_16x16x32_bf16 v[104:107], v[132:135], v[232:235], v[104:107]
	v_mfma_f32_16x16x32_bf16 v[88:91], v[132:135], v[240:243], v[88:91]
	v_mfma_f32_16x16x32_bf16 v[124:127], v[140:143], v[202:205], v[124:127]
	v_mfma_f32_16x16x32_bf16 v[112:115], v[140:143], v[224:227], v[112:115]
	v_mfma_f32_16x16x32_bf16 v[96:99], v[140:143], v[232:235], v[96:99]
	v_mfma_f32_16x16x32_bf16 v[80:83], v[140:143], v[240:243], v[80:83]
	v_mfma_f32_16x16x32_bf16 v[128:131], v[136:139], v[220:223], v[128:131]
	v_mfma_f32_16x16x32_bf16 v[120:123], v[136:139], v[228:231], v[120:123]
	v_mfma_f32_16x16x32_bf16 v[104:107], v[136:139], v[236:239], v[104:107]
	v_mfma_f32_16x16x32_bf16 v[88:91], v[136:139], v[244:247], v[88:91]
	v_mfma_f32_16x16x32_bf16 v[124:127], v[144:147], v[220:223], v[124:127]
	v_mfma_f32_16x16x32_bf16 v[112:115], v[144:147], v[228:231], v[112:115]
	v_mfma_f32_16x16x32_bf16 v[96:99], v[144:147], v[236:239], v[96:99]
	v_mfma_f32_16x16x32_bf16 v[80:83], v[144:147], v[244:247], v[80:83]
	s_setprio 0
	s_setprio 1
	v_mfma_f32_16x16x32_bf16 v[116:119], v[170:173], v[202:205], v[116:119]
	v_mfma_f32_16x16x32_bf16 v[100:103], v[170:173], v[224:227], v[100:103]
	v_mfma_f32_16x16x32_bf16 v[84:87], v[170:173], v[232:235], v[84:87]
	v_mfma_f32_16x16x32_bf16 v[72:75], v[170:173], v[240:243], v[72:75]
	v_mfma_f32_16x16x32_bf16 v[108:111], v[178:181], v[202:205], v[108:111]
	v_mfma_f32_16x16x32_bf16 v[92:95], v[178:181], v[224:227], v[92:95]
	v_mfma_f32_16x16x32_bf16 v[76:79], v[178:181], v[232:235], v[76:79]
	v_mfma_f32_16x16x32_bf16 v[68:71], v[178:181], v[240:243], v[68:71]
	v_mfma_f32_16x16x32_bf16 v[116:119], v[174:177], v[220:223], v[116:119]
	v_mfma_f32_16x16x32_bf16 v[100:103], v[174:177], v[228:231], v[100:103]
	v_mfma_f32_16x16x32_bf16 v[84:87], v[174:177], v[236:239], v[84:87]
	v_mfma_f32_16x16x32_bf16 v[72:75], v[174:177], v[244:247], v[72:75]
	v_mfma_f32_16x16x32_bf16 v[108:111], v[198:201], v[220:223], v[108:111]
	v_mfma_f32_16x16x32_bf16 v[92:95], v[198:201], v[228:231], v[92:95]
	v_mfma_f32_16x16x32_bf16 v[76:79], v[198:201], v[236:239], v[76:79]
	v_mfma_f32_16x16x32_bf16 v[68:71], v[198:201], v[244:247], v[68:71]
	s_setprio 0
	s_barrier
; #define PG8_STAGE(bufoff, gbase, voff) do { _Pragma("unroll") for (int _i = 0; _i < 2; ++_i) \
;         __builtin_amdgcn_global_load_lds((const unsigned*)((const char*)(gbase) + (voff)[_i]), (PG8_LAS unsigned*)(lds + (bufoff) + ldsw + _i * 8192), 16, 0, 0); } while (0)
; #define PG8_LDA(dst, b, h) do { _Pragma("unroll") for (int m = 0; m < 4; ++m) _Pragma("unroll") for (int k = 0; k < 2; ++k) dst[m][k] = *(const PG8_LAS bf16x8*)(lds + PG8_SA(b, h) + aoff + m * 2048 + k * 1024); } while (0)
; #define PG8_MMA(ai, bj, At, Bt) do { __builtin_amdgcn_s_setprio(1); _Pragma("unroll") for (int m = 0; m < 4; ++m) _Pragma("unroll") for (int n = 0; n < 2; ++n) _Pragma("unroll") for (int k = 0; k < 2; ++k) \
;         acc[ai][bj][m][n] = __builtin_amdgcn_mfma_f32_16x16x32_bf16(Bt[n][k], At[m][k], acc[ai][bj][m][n], 0, 0, 0); __builtin_amdgcn_s_setprio(0); } while (0)
; #define PG8_WAIT_V(n) asm volatile("s_waitcnt vmcnt(" #n ")" ::: "memory")
; #define PG8_WAIT_L(n) asm volatile("s_waitcnt lgkmcnt(" #n ")" ::: "memory")
; #define PG8_BAR __builtin_amdgcn_s_barrier()
; #define PG8_SCHED __builtin_amdgcn_sched_barrier(0)
; template <class Epi, class Sched, bool ALIGN_EPI = false, bool SP2 = false>
; __device__ __forceinline__ void gemm_phase(PG8_LAS unsigned char* lds, const Gemm g, const Sched& S, const Epi& E) {
;     ...
;             PG8_LDA(At, 1, 1); PG8_STAGE(PG8_SB(1, 0), b3, voffB); PG8_STAGE(PG8_SB(1, 1), b3 + hstep, voffB); PG8_STAGE(PG8_SA(1, 0), a3, voffA);
;             PG8_WAIT_V(8); PG8_WAIT_L(0); PG8_BAR; PG8_MMA(1, 0, At, B0); PG8_MMA(1, 1, At, B1); PG8_BAR; PG8_SCHED;
	s_add_i32 s18, s46, s24
	v_lshl_add_u64 v[166:167], v[166:167], 0, s[34:35]
	s_mov_b32 m0, s18
	ds_read_b128 v[202:205], v169 offset:49152
	ds_read_b128 v[220:223], v169 offset:50176
	ds_read_b128 v[224:227], v169 offset:51200
	ds_read_b128 v[228:231], v169 offset:52224
	ds_read_b128 v[232:235], v169 offset:53248
	ds_read_b128 v[236:239], v169 offset:54272
	ds_read_b128 v[240:243], v169 offset:55296
	ds_read_b128 v[244:247], v169 offset:56320
	global_load_lds_dwordx4 v[166:167], off
	s_add_i32 m0, s18, 0x2000
	s_add_u32 s16, s16, 0x80080
	v_lshl_add_u64 v[166:167], v[196:197], 0, s[34:35]
	s_addc_u32 s17, s17, 0
	s_add_i32 s18, s47, s24
	global_load_lds_dwordx4 v[166:167], off
	v_lshl_add_u64 v[166:167], s[16:17], 0, v[154:155]
	s_mov_b32 m0, s18
	s_nop 0
	global_load_lds_dwordx4 v[166:167], off
	v_lshl_add_u64 v[166:167], s[16:17], 0, v[150:151]
	s_add_i32 m0, s18, 0x2000
	s_nop 0
	global_load_lds_dwordx4 v[166:167], off
	v_lshl_add_u64 v[166:167], v[206:207], 0, s[34:35]
	s_mov_b32 m0, s33
	s_nop 0
	global_load_lds_dwordx4 v[166:167], off
	v_lshl_add_u64 v[166:167], v[184:185], 0, s[34:35]
	s_mov_b32 m0, s38
	s_nop 0
	global_load_lds_dwordx4 v[166:167], off
	s_waitcnt vmcnt(8)
	s_waitcnt lgkmcnt(0)
	s_barrier
	s_setprio 1
	s_waitcnt lgkmcnt(0)
	v_mfma_f32_16x16x32_bf16 v[64:67], v[132:135], v[202:205], v[64:67]
	v_mfma_f32_16x16x32_bf16 v[56:59], v[132:135], v[224:227], v[56:59]
	v_mfma_f32_16x16x32_bf16 v[40:43], v[132:135], v[232:235], v[40:43]
	v_mfma_f32_16x16x32_bf16 v[24:27], v[132:135], v[240:243], v[24:27]
	v_mfma_f32_16x16x32_bf16 v[60:63], v[140:143], v[202:205], v[60:63]
	v_mfma_f32_16x16x32_bf16 v[48:51], v[140:143], v[224:227], v[48:51]
	v_mfma_f32_16x16x32_bf16 v[32:35], v[140:143], v[232:235], v[32:35]
	v_mfma_f32_16x16x32_bf16 v[16:19], v[140:143], v[240:243], v[16:19]
	v_mfma_f32_16x16x32_bf16 v[64:67], v[136:139], v[220:223], v[64:67]
	v_mfma_f32_16x16x32_bf16 v[56:59], v[136:139], v[228:231], v[56:59]
	v_mfma_f32_16x16x32_bf16 v[40:43], v[136:139], v[236:239], v[40:43]
	v_mfma_f32_16x16x32_bf16 v[24:27], v[136:139], v[244:247], v[24:27]
	v_mfma_f32_16x16x32_bf16 v[60:63], v[144:147], v[220:223], v[60:63]
	v_mfma_f32_16x16x32_bf16 v[48:51], v[144:147], v[228:231], v[48:51]
	v_mfma_f32_16x16x32_bf16 v[32:35], v[144:147], v[236:239], v[32:35]
	v_mfma_f32_16x16x32_bf16 v[16:19], v[144:147], v[244:247], v[16:19]
	s_setprio 0
	s_setprio 1
	v_mfma_f32_16x16x32_bf16 v[52:55], v[170:173], v[202:205], v[52:55]
	v_mfma_f32_16x16x32_bf16 v[36:39], v[170:173], v[224:227], v[36:39]
	v_mfma_f32_16x16x32_bf16 v[20:23], v[170:173], v[232:235], v[20:23]
	v_mfma_f32_16x16x32_bf16 v[8:11], v[170:173], v[240:243], v[8:11]
	v_mfma_f32_16x16x32_bf16 v[44:47], v[178:181], v[202:205], v[44:47]
	v_mfma_f32_16x16x32_bf16 v[28:31], v[178:181], v[224:227], v[28:31]
	v_mfma_f32_16x16x32_bf16 v[12:15], v[178:181], v[232:235], v[12:15]
	v_mfma_f32_16x16x32_bf16 v[4:7], v[178:181], v[240:243], v[4:7]
	v_mfma_f32_16x16x32_bf16 v[52:55], v[174:177], v[220:223], v[52:55]
	v_mfma_f32_16x16x32_bf16 v[36:39], v[174:177], v[228:231], v[36:39]
	v_mfma_f32_16x16x32_bf16 v[20:23], v[174:177], v[236:239], v[20:23]
	v_mfma_f32_16x16x32_bf16 v[8:11], v[174:177], v[244:247], v[8:11]
	v_mfma_f32_16x16x32_bf16 v[44:47], v[198:201], v[220:223], v[44:47]
	v_mfma_f32_16x16x32_bf16 v[28:31], v[198:201], v[228:231], v[28:31]
	v_mfma_f32_16x16x32_bf16 v[12:15], v[198:201], v[236:239], v[12:15]
	v_mfma_f32_16x16x32_bf16 v[4:7], v[198:201], v[244:247], v[4:7]
	s_setprio 0
	s_barrier
	s_add_i32 s45, s45, 2
	s_add_u32 s14, s14, 0x100
	s_addc_u32 s15, s15, 0
	s_add_u32 s43, s43, 0x100
	s_addc_u32 s44, s44, 0
	s_cmp_gt_u32 s45, 29
	s_cbranch_scc0 .LBB11_1071
	s_and_b64 vcc, exec, s[4:5]
	s_cbranch_vccz .LBB11_1074
	s_barrier

; #define PG8_STAGE(bufoff, gbase, voff) do { _Pragma("unroll") for (int _i = 0; _i < 2; ++_i) \
;         __builtin_amdgcn_global_load_lds((const unsigned*)((const char*)(gbase) + (voff)[_i]), (PG8_LAS unsigned*)(lds + (bufoff) + ldsw + _i * 8192), 16, 0, 0); } while (0)
; #define PG8_LDA(dst, b, h) do { _Pragma("unroll") for (int m = 0; m < 4; ++m) _Pragma("unroll") for (int k = 0; k < 2; ++k) dst[m][k] = *(const PG8_LAS bf16x8*)(lds + PG8_SA(b, h) + aoff + m * 2048 + k * 1024); } while (0)
; #define PG8_LDB(dst, b, h) do { _Pragma("unroll") for (int n = 0; n < 2; ++n) _Pragma("unroll") for (int k = 0; k < 2; ++k) dst[n][k] = *(const PG8_LAS bf16x8*)(lds + PG8_SB(b, h) + boff + n * 2048 + k * 1024); } while (0)
; #define PG8_MMA(ai, bj, At, Bt) do { __builtin_amdgcn_s_setprio(1); _Pragma("unroll") for (int m = 0; m < 4; ++m) _Pragma("unroll") for (int n = 0; n < 2; ++n) _Pragma("unroll") for (int k = 0; k < 2; ++k) \
;         acc[ai][bj][m][n] = __builtin_amdgcn_mfma_f32_16x16x32_bf16(Bt[n][k], At[m][k], acc[ai][bj][m][n], 0, 0, 0); __builtin_amdgcn_s_setprio(0); } while (0)
; #define PG8_WAIT_V(n) asm volatile("s_waitcnt vmcnt(" #n ")" ::: "memory")
; #define PG8_WAIT_L(n) asm volatile("s_waitcnt lgkmcnt(" #n ")" ::: "memory")
; #define PG8_BAR __builtin_amdgcn_s_barrier()
; #define PG8_SCHED __builtin_amdgcn_sched_barrier(0)
; template <class Epi, class Sched, bool ALIGN_EPI = false, bool SP2 = false>
; __device__ __forceinline__ void gemm_phase(PG8_LAS unsigned char* lds, const Gemm g, const Sched& S, const Epi& E) {
;     ...
;             const char* a2 = last ? nA : cA + (size_t)(t + 2) * kstep; const char* b2 = last ? nB : cB + (size_t)(t + 2) * kstep;
;             const char* a3 = a2 + kstep; const char* b3 = b2 + kstep;
;             if (last && has_next) S.a_ready(nxt);
;             if constexpr (SP2) {
;             PG8_LDB(B0, 0, 0); PG8_LDB(B1, 0, 1); PG8_SCHED; PG8_LDA(At, 0, 0); PG8_STAGE(PG8_SA(1, 1), a1 + hstep, voffA);
;             PG8_WAIT_V(8); PG8_WAIT_L(0); PG8_BAR; PG8_MMA(0, 0, At, B0); PG8_MMA(0, 1, At, B1); PG8_BAR; PG8_SCHED;
;             PG8_LDA(At, 0, 1); PG8_STAGE(PG8_SB(0, 0), b2, voffB); PG8_STAGE(PG8_SB(0, 1), b2 + hstep, voffB); PG8_STAGE(PG8_SA(0, 0), a2, voffA);
;             PG8_WAIT_V(8); PG8_WAIT_L(0); PG8_BAR; PG8_MMA(1, 0, At, B0); PG8_MMA(1, 1, At, B1); PG8_BAR; PG8_SCHED;
.LBB11_1896:
	s_add_i32 s56, s22, 2
	s_add_u32 s57, s16, s20
	s_addc_u32 s23, s17, s21
	s_add_u32 s58, s14, s20
	s_addc_u32 s59, s15, s21
	s_add_i32 s60, 0, 0x10000
	s_cmp_eq_u32 s49, s22
	s_cselect_b32 s23, s5, s23
	s_cselect_b32 s22, s4, s57
	s_cselect_b32 s59, s19, s59
	s_cselect_b32 s58, s18, s58
	s_add_i32 s57, 0, 0x14000
	v_add_u32_e32 v156, s60, v1
	v_add_u32_e32 v174, s57, v1
	ds_read_b128 v[144:147], v156
	ds_read_b128 v[148:151], v156 offset:1024
	ds_read_b128 v[152:155], v156 offset:2048
	ds_read_b128 v[156:159], v156 offset:3072
	ds_read_b128 v[160:163], v174
	ds_read_b128 v[166:169], v174 offset:1024
	ds_read_b128 v[170:173], v174 offset:2048
	ds_read_b128 v[174:177], v174 offset:3072
	v_lshl_add_u64 v[184:185], s[16:17], 0, v[140:141]
	s_add_i32 m0, s45, 0xc000
	ds_read_b128 v[178:181], v143
	ds_read_b128 v[198:201], v143 offset:1024
	ds_read_b128 v[202:205], v143 offset:2048
	ds_read_b128 v[220:223], v143 offset:3072
	ds_read_b128 v[224:227], v143 offset:4096
	ds_read_b128 v[228:231], v143 offset:5120
	ds_read_b128 v[232:235], v143 offset:6144
	ds_read_b128 v[236:239], v143 offset:7168
	global_load_lds_dwordx4 v[184:185], off
	v_lshl_add_u64 v[184:185], s[16:17], 0, v[138:139]
	s_add_i32 m0, s45, 0xe000
	s_nop 0
	global_load_lds_dwordx4 v[184:185], off
	s_waitcnt vmcnt(8)
	s_waitcnt lgkmcnt(0)
	s_barrier
	s_setprio 1
	s_waitcnt lgkmcnt(0)
	v_mfma_f32_16x16x32_bf16 v[100:103], v[144:147], v[178:181], v[100:103]
	v_mfma_f32_16x16x32_bf16 v[116:119], v[144:147], v[202:205], v[116:119]
	v_mfma_f32_16x16x32_bf16 v[124:127], v[144:147], v[224:227], v[124:127]
	v_mfma_f32_16x16x32_bf16 v[128:131], v[144:147], v[232:235], v[128:131]
	v_mfma_f32_16x16x32_bf16 v[68:71], v[152:155], v[178:181], v[68:71]
	v_mfma_f32_16x16x32_bf16 v[80:83], v[152:155], v[202:205], v[80:83]
	v_mfma_f32_16x16x32_bf16 v[104:107], v[152:155], v[224:227], v[104:107]
	v_mfma_f32_16x16x32_bf16 v[120:123], v[152:155], v[232:235], v[120:123]
	v_mfma_f32_16x16x32_bf16 v[100:103], v[148:151], v[198:201], v[100:103]
	v_mfma_f32_16x16x32_bf16 v[116:119], v[148:151], v[220:223], v[116:119]
	v_mfma_f32_16x16x32_bf16 v[124:127], v[148:151], v[228:231], v[124:127]
	v_mfma_f32_16x16x32_bf16 v[128:131], v[148:151], v[236:239], v[128:131]
	v_mfma_f32_16x16x32_bf16 v[68:71], v[156:159], v[198:201], v[68:71]
	v_mfma_f32_16x16x32_bf16 v[80:83], v[156:159], v[220:223], v[80:83]
	v_mfma_f32_16x16x32_bf16 v[104:107], v[156:159], v[228:231], v[104:107]
	v_mfma_f32_16x16x32_bf16 v[120:123], v[156:159], v[236:239], v[120:123]
	s_setprio 0
	s_setprio 1
	v_mfma_f32_16x16x32_bf16 v[16:19], v[160:163], v[178:181], v[16:19]
	v_mfma_f32_16x16x32_bf16 v[32:35], v[160:163], v[202:205], v[32:35]
	v_mfma_f32_16x16x32_bf16 v[48:51], v[160:163], v[224:227], v[48:51]
	v_mfma_f32_16x16x32_bf16 v[76:79], v[160:163], v[232:235], v[76:79]
	v_mfma_f32_16x16x32_bf16 v[4:7], v[170:173], v[178:181], v[4:7]
	v_mfma_f32_16x16x32_bf16 v[8:11], v[170:173], v[202:205], v[8:11]
	v_mfma_f32_16x16x32_bf16 v[12:15], v[170:173], v[224:227], v[12:15]
	v_mfma_f32_16x16x32_bf16 v[24:27], v[170:173], v[232:235], v[24:27]
	v_mfma_f32_16x16x32_bf16 v[16:19], v[166:169], v[198:201], v[16:19]
	v_mfma_f32_16x16x32_bf16 v[32:35], v[166:169], v[220:223], v[32:35]
	v_mfma_f32_16x16x32_bf16 v[48:51], v[166:169], v[228:231], v[48:51]
	v_mfma_f32_16x16x32_bf16 v[76:79], v[166:169], v[236:239], v[76:79]
	v_mfma_f32_16x16x32_bf16 v[4:7], v[174:177], v[198:201], v[4:7]
	v_mfma_f32_16x16x32_bf16 v[8:11], v[174:177], v[220:223], v[8:11]
	v_mfma_f32_16x16x32_bf16 v[12:15], v[174:177], v[228:231], v[12:15]
	v_mfma_f32_16x16x32_bf16 v[24:27], v[174:177], v[236:239], v[24:27]
	s_setprio 0
	s_barrier
	s_add_i32 s60, s60, s13
	v_lshl_add_u64 v[184:185], s[58:59], 0, v[2:3]
	s_mov_b32 m0, s60
	ds_read_b128 v[178:181], v143 offset:16384
	ds_read_b128 v[198:201], v143 offset:17408
	ds_read_b128 v[202:205], v143 offset:18432
	ds_read_b128 v[220:223], v143 offset:19456
	ds_read_b128 v[224:227], v143 offset:20480
	ds_read_b128 v[228:231], v143 offset:21504
	ds_read_b128 v[232:235], v143 offset:22528
	ds_read_b128 v[236:239], v143 offset:23552
	global_load_lds_dwordx4 v[184:185], off
	s_add_i32 m0, s60, 0x2000
	v_lshl_add_u64 v[186:187], s[58:59], 0, v[132:133]
	s_add_u32 s58, s58, s33
	s_addc_u32 s59, s59, 0
	s_add_i32 s57, s57, s13
	global_load_lds_dwordx4 v[186:187], off
	v_lshl_add_u64 v[196:197], s[58:59], 0, v[2:3]
	s_mov_b32 m0, s57
	v_lshl_add_u64 v[206:207], s[58:59], 0, v[132:133]
	global_load_lds_dwordx4 v[196:197], off
	s_add_i32 m0, s57, 0x2000
	v_lshl_add_u64 v[240:241], s[22:23], 0, v[2:3]
	global_load_lds_dwordx4 v[206:207], off
	s_mov_b32 m0, s45
	v_lshl_add_u64 v[242:243], s[22:23], 0, v[132:133]
	global_load_lds_dwordx4 v[240:241], off
	s_mov_b32 m0, s46
	s_nop 0
	global_load_lds_dwordx4 v[242:243], off
	s_waitcnt vmcnt(8)
	s_waitcnt lgkmcnt(0)
	s_barrier
; #define PG8_STAGE(bufoff, gbase, voff) do { _Pragma("unroll") for (int _i = 0; _i < 2; ++_i) \
;         __builtin_amdgcn_global_load_lds((const unsigned*)((const char*)(gbase) + (voff)[_i]), (PG8_LAS unsigned*)(lds + (bufoff) + ldsw + _i * 8192), 16, 0, 0); } while (0)
; #define PG8_LDA(dst, b, h) do { _Pragma("unroll") for (int m = 0; m < 4; ++m) _Pragma("unroll") for (int k = 0; k < 2; ++k) dst[m][k] = *(const PG8_LAS bf16x8*)(lds + PG8_SA(b, h) + aoff + m * 2048 + k * 1024); } while (0)
; #define PG8_LDB(dst, b, h) do { _Pragma("unroll") for (int n = 0; n < 2; ++n) _Pragma("unroll") for (int k = 0; k < 2; ++k) dst[n][k] = *(const PG8_LAS bf16x8*)(lds + PG8_SB(b, h) + boff + n * 2048 + k * 1024); } while (0)
; #define PG8_MMA(ai, bj, At, Bt) do { __builtin_amdgcn_s_setprio(1); _Pragma("unroll") for (int m = 0; m < 4; ++m) _Pragma("unroll") for (int n = 0; n < 2; ++n) _Pragma("unroll") for (int k = 0; k < 2; ++k) \
;         acc[ai][bj][m][n] = __builtin_amdgcn_mfma_f32_16x16x32_bf16(Bt[n][k], At[m][k], acc[ai][bj][m][n], 0, 0, 0); __builtin_amdgcn_s_setprio(0); } while (0)
; #define PG8_WAIT_V(n) asm volatile("s_waitcnt vmcnt(" #n ")" ::: "memory")
; #define PG8_WAIT_L(n) asm volatile("s_waitcnt lgkmcnt(" #n ")" ::: "memory")
; #define PG8_BAR __builtin_amdgcn_s_barrier()
; #define PG8_SCHED __builtin_amdgcn_sched_barrier(0)
; template <class Epi, class Sched, bool ALIGN_EPI = false, bool SP2 = false>
; __device__ __forceinline__ void gemm_phase(PG8_LAS unsigned char* lds, const Gemm g, const Sched& S, const Epi& E) {
;     ...
;             PG8_WAIT_V(8); PG8_WAIT_L(0); PG8_BAR; PG8_MMA(1, 0, At, B0); PG8_MMA(1, 1, At, B1); PG8_BAR; PG8_SCHED;
;             PG8_LDB(B0, 1, 0); PG8_LDB(B1, 1, 1); PG8_SCHED; PG8_LDA(At, 1, 0); PG8_STAGE(PG8_SA(0, 1), a2 + hstep, voffA);
;             PG8_WAIT_V(8); PG8_WAIT_L(0); PG8_BAR; PG8_MMA(0, 0, At, B0); PG8_MMA(0, 1, At, B1); PG8_BAR; PG8_SCHED;
	s_setprio 1
	s_waitcnt lgkmcnt(0)
	v_mfma_f32_16x16x32_bf16 v[108:111], v[144:147], v[178:181], v[108:111]
	v_mfma_f32_16x16x32_bf16 v[88:91], v[144:147], v[202:205], v[88:91]
	v_mfma_f32_16x16x32_bf16 v[60:63], v[144:147], v[224:227], v[60:63]
	v_mfma_f32_16x16x32_bf16 v[36:39], v[144:147], v[232:235], v[36:39]
	v_mfma_f32_16x16x32_bf16 v[112:115], v[152:155], v[178:181], v[112:115]
	v_mfma_f32_16x16x32_bf16 v[92:95], v[152:155], v[202:205], v[92:95]
	v_mfma_f32_16x16x32_bf16 v[64:67], v[152:155], v[224:227], v[64:67]
	v_mfma_f32_16x16x32_bf16 v[40:43], v[152:155], v[232:235], v[40:43]
	v_mfma_f32_16x16x32_bf16 v[108:111], v[148:151], v[198:201], v[108:111]
	v_mfma_f32_16x16x32_bf16 v[88:91], v[148:151], v[220:223], v[88:91]
	v_mfma_f32_16x16x32_bf16 v[60:63], v[148:151], v[228:231], v[60:63]
	v_mfma_f32_16x16x32_bf16 v[36:39], v[148:151], v[236:239], v[36:39]
	v_mfma_f32_16x16x32_bf16 v[112:115], v[156:159], v[198:201], v[112:115]
	v_mfma_f32_16x16x32_bf16 v[92:95], v[156:159], v[220:223], v[92:95]
	v_mfma_f32_16x16x32_bf16 v[64:67], v[156:159], v[228:231], v[64:67]
	v_mfma_f32_16x16x32_bf16 v[40:43], v[156:159], v[236:239], v[40:43]
	s_setprio 0
	s_setprio 1
	v_mfma_f32_16x16x32_bf16 v[96:99], v[160:163], v[178:181], v[96:99]
	v_mfma_f32_16x16x32_bf16 v[84:87], v[160:163], v[202:205], v[84:87]
	v_mfma_f32_16x16x32_bf16 v[56:59], v[160:163], v[224:227], v[56:59]
	v_mfma_f32_16x16x32_bf16 v[28:31], v[160:163], v[232:235], v[28:31]
	v_mfma_f32_16x16x32_bf16 v[44:47], v[170:173], v[178:181], v[44:47]
	v_mfma_f32_16x16x32_bf16 v[72:75], v[170:173], v[202:205], v[72:75]
	v_mfma_f32_16x16x32_bf16 v[52:55], v[170:173], v[224:227], v[52:55]
	v_mfma_f32_16x16x32_bf16 v[20:23], v[170:173], v[232:235], v[20:23]
	v_mfma_f32_16x16x32_bf16 v[96:99], v[166:169], v[198:201], v[96:99]
	v_mfma_f32_16x16x32_bf16 v[84:87], v[166:169], v[220:223], v[84:87]
	v_mfma_f32_16x16x32_bf16 v[56:59], v[166:169], v[228:231], v[56:59]
	v_mfma_f32_16x16x32_bf16 v[28:31], v[166:169], v[236:239], v[28:31]
	v_mfma_f32_16x16x32_bf16 v[44:47], v[174:177], v[198:201], v[44:47]
	v_mfma_f32_16x16x32_bf16 v[72:75], v[174:177], v[220:223], v[72:75]
	v_mfma_f32_16x16x32_bf16 v[52:55], v[174:177], v[228:231], v[52:55]
	v_mfma_f32_16x16x32_bf16 v[20:23], v[174:177], v[236:239], v[20:23]
	s_setprio 0
	s_barrier
	s_add_i32 s57, 0, 0x18000
	s_add_i32 s58, 0, 0x1c000
	v_add_u32_e32 v156, s57, v1
	v_add_u32_e32 v174, s58, v1
	ds_read_b128 v[144:147], v156
	ds_read_b128 v[148:151], v156 offset:1024
	ds_read_b128 v[152:155], v156 offset:2048
	ds_read_b128 v[156:159], v156 offset:3072
	ds_read_b128 v[160:163], v174
	ds_read_b128 v[166:169], v174 offset:1024
	ds_read_b128 v[170:173], v174 offset:2048
	ds_read_b128 v[174:177], v174 offset:3072
	s_add_u32 s22, s22, s33
	s_addc_u32 s23, s23, 0
	s_mov_b32 m0, s47
	v_lshl_add_u64 v[244:245], s[22:23], 0, v[2:3]
	ds_read_b128 v[178:181], v143 offset:32768
	ds_read_b128 v[198:201], v143 offset:33792
	ds_read_b128 v[202:205], v143 offset:34816
	ds_read_b128 v[220:223], v143 offset:35840
	ds_read_b128 v[224:227], v143 offset:36864
	ds_read_b128 v[228:231], v143 offset:37888
	ds_read_b128 v[232:235], v143 offset:38912
	ds_read_b128 v[236:239], v143 offset:39936
	global_load_lds_dwordx4 v[244:245], off
	v_lshl_add_u64 v[244:245], s[22:23], 0, v[132:133]
	s_mov_b32 m0, s48
	s_nop 0
	global_load_lds_dwordx4 v[244:245], off
	s_waitcnt vmcnt(8)
	s_waitcnt lgkmcnt(0)
	s_barrier
	s_setprio 1
	s_waitcnt lgkmcnt(0)
	v_mfma_f32_16x16x32_bf16 v[100:103], v[144:147], v[178:181], v[100:103]
	v_mfma_f32_16x16x32_bf16 v[116:119], v[144:147], v[202:205], v[116:119]
	v_mfma_f32_16x16x32_bf16 v[124:127], v[144:147], v[224:227], v[124:127]
	v_mfma_f32_16x16x32_bf16 v[128:131], v[144:147], v[232:235], v[128:131]
	v_mfma_f32_16x16x32_bf16 v[68:71], v[152:155], v[178:181], v[68:71]
	v_mfma_f32_16x16x32_bf16 v[80:83], v[152:155], v[202:205], v[80:83]
	v_mfma_f32_16x16x32_bf16 v[104:107], v[152:155], v[224:227], v[104:107]
	v_mfma_f32_16x16x32_bf16 v[120:123], v[152:155], v[232:235], v[120:123]
	v_mfma_f32_16x16x32_bf16 v[100:103], v[148:151], v[198:201], v[100:103]
	v_mfma_f32_16x16x32_bf16 v[116:119], v[148:151], v[220:223], v[116:119]
	v_mfma_f32_16x16x32_bf16 v[124:127], v[148:151], v[228:231], v[124:127]
	v_mfma_f32_16x16x32_bf16 v[128:131], v[148:151], v[236:239], v[128:131]
	v_mfma_f32_16x16x32_bf16 v[68:71], v[156:159], v[198:201], v[68:71]
	v_mfma_f32_16x16x32_bf16 v[80:83], v[156:159], v[220:223], v[80:83]
	v_mfma_f32_16x16x32_bf16 v[104:107], v[156:159], v[228:231], v[104:107]
	v_mfma_f32_16x16x32_bf16 v[120:123], v[156:159], v[236:239], v[120:123]
	s_setprio 0
	s_setprio 1
	v_mfma_f32_16x16x32_bf16 v[16:19], v[160:163], v[178:181], v[16:19]
	v_mfma_f32_16x16x32_bf16 v[32:35], v[160:163], v[202:205], v[32:35]
	v_mfma_f32_16x16x32_bf16 v[48:51], v[160:163], v[224:227], v[48:51]
	v_mfma_f32_16x16x32_bf16 v[76:79], v[160:163], v[232:235], v[76:79]
	v_mfma_f32_16x16x32_bf16 v[4:7], v[170:173], v[178:181], v[4:7]
	v_mfma_f32_16x16x32_bf16 v[8:11], v[170:173], v[202:205], v[8:11]
	v_mfma_f32_16x16x32_bf16 v[12:15], v[170:173], v[224:227], v[12:15]
	v_mfma_f32_16x16x32_bf16 v[24:27], v[170:173], v[232:235], v[24:27]
	v_mfma_f32_16x16x32_bf16 v[16:19], v[166:169], v[198:201], v[16:19]
	v_mfma_f32_16x16x32_bf16 v[32:35], v[166:169], v[220:223], v[32:35]
	v_mfma_f32_16x16x32_bf16 v[48:51], v[166:169], v[228:231], v[48:51]
	v_mfma_f32_16x16x32_bf16 v[76:79], v[166:169], v[236:239], v[76:79]
	v_mfma_f32_16x16x32_bf16 v[4:7], v[174:177], v[198:201], v[4:7]
	v_mfma_f32_16x16x32_bf16 v[8:11], v[174:177], v[220:223], v[8:11]
	v_mfma_f32_16x16x32_bf16 v[12:15], v[174:177], v[228:231], v[12:15]
	v_mfma_f32_16x16x32_bf16 v[24:27], v[174:177], v[236:239], v[24:27]
	s_setprio 0
	s_barrier
; #define PG8_STAGE(bufoff, gbase, voff) do { _Pragma("unroll") for (int _i = 0; _i < 2; ++_i) \
;         __builtin_amdgcn_global_load_lds((const unsigned*)((const char*)(gbase) + (voff)[_i]), (PG8_LAS unsigned*)(lds + (bufoff) + ldsw + _i * 8192), 16, 0, 0); } while (0)
; #define PG8_LDA(dst, b, h) do { _Pragma("unroll") for (int m = 0; m < 4; ++m) _Pragma("unroll") for (int k = 0; k < 2; ++k) dst[m][k] = *(const PG8_LAS bf16x8*)(lds + PG8_SA(b, h) + aoff + m * 2048 + k * 1024); } while (0)
; #define PG8_MMA(ai, bj, At, Bt) do { __builtin_amdgcn_s_setprio(1); _Pragma("unroll") for (int m = 0; m < 4; ++m) _Pragma("unroll") for (int n = 0; n < 2; ++n) _Pragma("unroll") for (int k = 0; k < 2; ++k) \
;         acc[ai][bj][m][n] = __builtin_amdgcn_mfma_f32_16x16x32_bf16(Bt[n][k], At[m][k], acc[ai][bj][m][n], 0, 0, 0); __builtin_amdgcn_s_setprio(0); } while (0)
; #define PG8_WAIT_V(n) asm volatile("s_waitcnt vmcnt(" #n ")" ::: "memory")
; #define PG8_WAIT_L(n) asm volatile("s_waitcnt lgkmcnt(" #n ")" ::: "memory")
; #define PG8_BAR __builtin_amdgcn_s_barrier()
; #define PG8_SCHED __builtin_amdgcn_sched_barrier(0)
; template <class Epi, class Sched, bool ALIGN_EPI = false, bool SP2 = false>
; __device__ __forceinline__ void gemm_phase(PG8_LAS unsigned char* lds, const Gemm g, const Sched& S, const Epi& E) {
;     ...
;             PG8_LDA(At, 1, 1); PG8_STAGE(PG8_SB(1, 0), b3, voffB); PG8_STAGE(PG8_SB(1, 1), b3 + hstep, voffB); PG8_STAGE(PG8_SA(1, 0), a3, voffA);
;             PG8_WAIT_V(8); PG8_WAIT_L(0); PG8_BAR; PG8_MMA(1, 0, At, B0); PG8_MMA(1, 1, At, B1); PG8_BAR; PG8_SCHED;
;     ...
;         if (!has_next) break;
; #pragma unroll
;         for (int a = 0; a < 2; ++a)
; #pragma unroll
;             for (int b = 0; b < 2; ++b)
; #pragma unroll
;                 for (int m = 0; m < 4; ++m)
; #pragma unroll
;                     for (int n = 0; n < 2; ++n) acc[a][b][m][n] = (f32x4){0.f, 0.f, 0.f, 0.f};
;         cur = nxt; cA = nA; cB = nB; ++ui;
	s_add_i32 s22, s57, s13
	v_lshl_add_u64 v[184:185], v[184:185], 0, s[34:35]
	s_mov_b32 m0, s22
	ds_read_b128 v[178:181], v143 offset:49152
	ds_read_b128 v[198:201], v143 offset:50176
	ds_read_b128 v[202:205], v143 offset:51200
	ds_read_b128 v[220:223], v143 offset:52224
	ds_read_b128 v[224:227], v143 offset:53248
	ds_read_b128 v[228:231], v143 offset:54272
	ds_read_b128 v[232:235], v143 offset:55296
	ds_read_b128 v[236:239], v143 offset:56320
	global_load_lds_dwordx4 v[184:185], off
	v_lshl_add_u64 v[184:185], v[186:187], 0, s[34:35]
	s_add_i32 m0, s22, 0x2000
	s_add_i32 s22, s58, s13
	global_load_lds_dwordx4 v[184:185], off
	v_lshl_add_u64 v[184:185], v[196:197], 0, s[34:35]
	s_mov_b32 m0, s22
	s_nop 0
	global_load_lds_dwordx4 v[184:185], off
	v_lshl_add_u64 v[184:185], v[206:207], 0, s[34:35]
	s_add_i32 m0, s22, 0x2000
	s_nop 0
	global_load_lds_dwordx4 v[184:185], off
	v_lshl_add_u64 v[184:185], v[240:241], 0, s[34:35]
	s_mov_b32 m0, s50
	s_nop 0
	global_load_lds_dwordx4 v[184:185], off
	v_lshl_add_u64 v[184:185], v[242:243], 0, s[34:35]
	s_mov_b32 m0, s51
	s_nop 0
	global_load_lds_dwordx4 v[184:185], off
	s_waitcnt vmcnt(8)
	s_waitcnt lgkmcnt(0)
	s_barrier
	s_setprio 1
	s_waitcnt lgkmcnt(0)
	v_mfma_f32_16x16x32_bf16 v[108:111], v[144:147], v[178:181], v[108:111]
	v_mfma_f32_16x16x32_bf16 v[88:91], v[144:147], v[202:205], v[88:91]
	v_mfma_f32_16x16x32_bf16 v[60:63], v[144:147], v[224:227], v[60:63]
	v_mfma_f32_16x16x32_bf16 v[36:39], v[144:147], v[232:235], v[36:39]
	v_mfma_f32_16x16x32_bf16 v[112:115], v[152:155], v[178:181], v[112:115]
	v_mfma_f32_16x16x32_bf16 v[92:95], v[152:155], v[202:205], v[92:95]
	v_mfma_f32_16x16x32_bf16 v[64:67], v[152:155], v[224:227], v[64:67]
	v_mfma_f32_16x16x32_bf16 v[40:43], v[152:155], v[232:235], v[40:43]
	v_mfma_f32_16x16x32_bf16 v[108:111], v[148:151], v[198:201], v[108:111]
	v_mfma_f32_16x16x32_bf16 v[88:91], v[148:151], v[220:223], v[88:91]
	v_mfma_f32_16x16x32_bf16 v[60:63], v[148:151], v[228:231], v[60:63]
	v_mfma_f32_16x16x32_bf16 v[36:39], v[148:151], v[236:239], v[36:39]
	v_mfma_f32_16x16x32_bf16 v[112:115], v[156:159], v[198:201], v[112:115]
	v_mfma_f32_16x16x32_bf16 v[92:95], v[156:159], v[220:223], v[92:95]
	v_mfma_f32_16x16x32_bf16 v[64:67], v[156:159], v[228:231], v[64:67]
	v_mfma_f32_16x16x32_bf16 v[40:43], v[156:159], v[236:239], v[40:43]
	s_setprio 0
	s_setprio 1
	v_mfma_f32_16x16x32_bf16 v[96:99], v[160:163], v[178:181], v[96:99]
	v_mfma_f32_16x16x32_bf16 v[84:87], v[160:163], v[202:205], v[84:87]
	v_mfma_f32_16x16x32_bf16 v[56:59], v[160:163], v[224:227], v[56:59]
	v_mfma_f32_16x16x32_bf16 v[28:31], v[160:163], v[232:235], v[28:31]
	v_mfma_f32_16x16x32_bf16 v[44:47], v[170:173], v[178:181], v[44:47]
	v_mfma_f32_16x16x32_bf16 v[72:75], v[170:173], v[202:205], v[72:75]
	v_mfma_f32_16x16x32_bf16 v[52:55], v[170:173], v[224:227], v[52:55]
	v_mfma_f32_16x16x32_bf16 v[20:23], v[170:173], v[232:235], v[20:23]
	v_mfma_f32_16x16x32_bf16 v[96:99], v[166:169], v[198:201], v[96:99]
	v_mfma_f32_16x16x32_bf16 v[84:87], v[166:169], v[220:223], v[84:87]
	v_mfma_f32_16x16x32_bf16 v[56:59], v[166:169], v[228:231], v[56:59]
	v_mfma_f32_16x16x32_bf16 v[28:31], v[166:169], v[236:239], v[28:31]
	v_mfma_f32_16x16x32_bf16 v[44:47], v[174:177], v[198:201], v[44:47]
	v_mfma_f32_16x16x32_bf16 v[72:75], v[174:177], v[220:223], v[72:75]
	v_mfma_f32_16x16x32_bf16 v[52:55], v[174:177], v[228:231], v[52:55]
	v_mfma_f32_16x16x32_bf16 v[20:23], v[174:177], v[236:239], v[20:23]
	s_setprio 0
	s_barrier
	s_add_u32 s20, s20, 0x100
	s_addc_u32 s21, s21, 0
	v_lshl_add_u64 v[140:141], v[140:141], 0, s[62:63]
	v_lshl_add_u64 v[138:139], v[138:139], 0, s[62:63]
	s_cmp_ge_u32 s56, s29
	s_mov_b32 s22, s56
	s_cbranch_scc0 .LBB11_1896
	s_and_b64 vcc, exec, s[38:39]
	s_cbranch_vccnz .LBB11_1884
	v_mov_b32_e32 v20, 0
	s_mov_b32 s42, s53
	s_mov_b32 s28, s54
	s_mov_b64 s[14:15], s[18:19]
	s_mov_b64 s[16:17], s[4:5]
	s_mov_b32 s52, s55
	v_mov_b32_e32 v21, v20
	v_mov_b32_e32 v22, v20
	v_mov_b32_e32 v23, v20
	v_mov_b32_e32 v28, v20
	v_mov_b32_e32 v29, v20
	v_mov_b32_e32 v30, v20
	v_mov_b32_e32 v31, v20
	v_mov_b32_e32 v52, v20
	v_mov_b32_e32 v53, v20
	v_mov_b32_e32 v54, v20
	v_mov_b32_e32 v55, v20
	v_mov_b32_e32 v56, v20
	v_mov_b32_e32 v57, v20
	v_mov_b32_e32 v58, v20
	v_mov_b32_e32 v59, v20
	v_mov_b32_e32 v72, v20
	v_mov_b32_e32 v73, v20
	v_mov_b32_e32 v74, v20
	v_mov_b32_e32 v75, v20
	v_mov_b32_e32 v84, v20
	v_mov_b32_e32 v85, v20
	v_mov_b32_e32 v86, v20
	v_mov_b32_e32 v87, v20
	v_mov_b32_e32 v44, v20
	v_mov_b32_e32 v45, v20
	v_mov_b32_e32 v46, v20
	v_mov_b32_e32 v47, v20
	v_mov_b32_e32 v96, v20
	v_mov_b32_e32 v97, v20
	v_mov_b32_e32 v98, v20
	v_mov_b32_e32 v99, v20
	v_mov_b32_e32 v40, v20
	v_mov_b32_e32 v41, v20
	v_mov_b32_e32 v42, v20
	v_mov_b32_e32 v43, v20
	v_mov_b32_e32 v36, v20
	v_mov_b32_e32 v37, v20
	v_mov_b32_e32 v38, v20
	v_mov_b32_e32 v39, v20
	v_mov_b32_e32 v64, v20
	v_mov_b32_e32 v65, v20
	v_mov_b32_e32 v66, v20
	v_mov_b32_e32 v67, v20
	v_mov_b32_e32 v60, v20
	v_mov_b32_e32 v61, v20
	v_mov_b32_e32 v62, v20
	v_mov_b32_e32 v63, v20
	v_mov_b32_e32 v92, v20
	v_mov_b32_e32 v93, v20
	v_mov_b32_e32 v94, v20
	v_mov_b32_e32 v95, v20
	v_mov_b32_e32 v88, v20
	v_mov_b32_e32 v89, v20
	v_mov_b32_e32 v90, v20
	v_mov_b32_e32 v91, v20
	v_mov_b32_e32 v112, v20
	v_mov_b32_e32 v113, v20
	v_mov_b32_e32 v114, v20
	v_mov_b32_e32 v115, v20
	v_mov_b32_e32 v108, v20
	v_mov_b32_e32 v109, v20
	v_mov_b32_e32 v110, v20
	v_mov_b32_e32 v111, v20
	v_mov_b32_e32 v24, v20
	v_mov_b32_e32 v25, v20
	v_mov_b32_e32 v26, v20
	v_mov_b32_e32 v27, v20
	v_mov_b32_e32 v76, v20
	v_mov_b32_e32 v77, v20
	v_mov_b32_e32 v78, v20
	v_mov_b32_e32 v79, v20
	v_mov_b32_e32 v12, v20
	v_mov_b32_e32 v13, v20
	v_mov_b32_e32 v14, v20
	v_mov_b32_e32 v15, v20
	v_mov_b32_e32 v48, v20
	v_mov_b32_e32 v49, v20
	v_mov_b32_e32 v50, v20
	v_mov_b32_e32 v51, v20
	v_mov_b32_e32 v8, v20
	v_mov_b32_e32 v9, v20
	v_mov_b32_e32 v10, v20
	v_mov_b32_e32 v11, v20
	v_mov_b32_e32 v32, v20
	v_mov_b32_e32 v33, v20
	v_mov_b32_e32 v34, v20
	v_mov_b32_e32 v35, v20
	v_mov_b32_e32 v4, v20
	v_mov_b32_e32 v5, v20
	v_mov_b32_e32 v6, v20
	v_mov_b32_e32 v7, v20
	v_mov_b32_e32 v16, v20
	v_mov_b32_e32 v17, v20
	v_mov_b32_e32 v18, v20
	v_mov_b32_e32 v19, v20
	v_mov_b32_e32 v120, v20
	v_mov_b32_e32 v121, v20
	v_mov_b32_e32 v122, v20
	v_mov_b32_e32 v123, v20
	v_mov_b32_e32 v128, v20
	v_mov_b32_e32 v129, v20
	v_mov_b32_e32 v130, v20
	v_mov_b32_e32 v131, v20
	v_mov_b32_e32 v104, v20
	v_mov_b32_e32 v105, v20
	v_mov_b32_e32 v106, v20
	v_mov_b32_e32 v107, v20
	v_mov_b32_e32 v124, v20
	v_mov_b32_e32 v125, v20
	v_mov_b32_e32 v126, v20
	v_mov_b32_e32 v127, v20
	v_mov_b32_e32 v80, v20
	v_mov_b32_e32 v81, v20
	v_mov_b32_e32 v82, v20
	v_mov_b32_e32 v83, v20
	v_mov_b32_e32 v116, v20
	v_mov_b32_e32 v117, v20
	v_mov_b32_e32 v118, v20
	v_mov_b32_e32 v119, v20
	v_mov_b32_e32 v68, v20
	v_mov_b32_e32 v69, v20
	v_mov_b32_e32 v70, v20
	v_mov_b32_e32 v71, v20
	v_mov_b32_e32 v100, v20
	v_mov_b32_e32 v101, v20
	v_mov_b32_e32 v102, v20
	v_mov_b32_e32 v103, v20
	s_branch .LBB11_1884
